# LDS-DMA loads in all six GEMM K-loops use the saddr form (scalar base + 32-bit VGPR offset): removes the 64-bit VALU address adds from the load segments
# speedup vs baseline: 1.0107x; 1.0107x over previous
.LBB0_146:
	s_add_u32 s40, s34, 0xfff80080
	s_addc_u32 s41, s35, -1
	s_add_i32 s61, 0, 0x10000
	s_cmp_eq_u32 s60, 28
	s_cselect_b32 s43, s13, s41
	s_cselect_b32 s42, s56, s40
	s_cselect_b32 s41, s9, s59
	s_cselect_b32 s40, s57, s58
	s_add_i32 s64, 0, 0x14000
	v_add_u32_e32 v160, s61, v143
	v_add_u32_e32 v176, s64, v143
	ds_read_b128 v[148:151], v160
	ds_read_b128 v[152:155], v160 offset:1024
	ds_read_b128 v[156:159], v160 offset:2048
	ds_read_b128 v[160:163], v160 offset:3072
	ds_read_b128 v[164:167], v176
	ds_read_b128 v[168:171], v176 offset:1024
	ds_read_b128 v[172:175], v176 offset:2048
	ds_read_b128 v[176:179], v176 offset:3072
	s_add_i32 m0, s47, 0xc000
	ds_read_b128 v[180:183], v147
	ds_read_b128 v[184:187], v147 offset:1024
	ds_read_b128 v[188:191], v147 offset:2048
	ds_read_b128 v[192:195], v147 offset:3072
	ds_read_b128 v[202:205], v147 offset:4096
	ds_read_b128 v[214:217], v147 offset:5120
	ds_read_b128 v[218:221], v147 offset:6144
	ds_read_b128 v[222:225], v147 offset:7168
	global_load_lds_dwordx4 v138, s[34:35]
	s_add_i32 m0, s47, 0xe000
	s_nop 0
	global_load_lds_dwordx4 v140, s[34:35]
	s_waitcnt vmcnt(8)
	s_waitcnt lgkmcnt(0)
	s_barrier
	s_setprio 1
	s_waitcnt lgkmcnt(0)
	v_mfma_f32_16x16x32_bf16 v[128:131], v[148:151], v[180:183], v[128:131]
	v_mfma_f32_16x16x32_bf16 v[120:123], v[156:159], v[180:183], v[120:123]
	v_mfma_f32_16x16x32_bf16 v[112:115], v[148:151], v[188:191], v[112:115]
	v_mfma_f32_16x16x32_bf16 v[104:107], v[156:159], v[188:191], v[104:107]
	v_mfma_f32_16x16x32_bf16 v[96:99], v[148:151], v[202:205], v[96:99]
	v_mfma_f32_16x16x32_bf16 v[88:91], v[156:159], v[202:205], v[88:91]
	v_mfma_f32_16x16x32_bf16 v[80:83], v[148:151], v[218:221], v[80:83]
	v_mfma_f32_16x16x32_bf16 v[72:75], v[156:159], v[218:221], v[72:75]
	v_mfma_f32_16x16x32_bf16 v[128:131], v[152:155], v[184:187], v[128:131]
	v_mfma_f32_16x16x32_bf16 v[120:123], v[160:163], v[184:187], v[120:123]
	v_mfma_f32_16x16x32_bf16 v[112:115], v[152:155], v[192:195], v[112:115]
	v_mfma_f32_16x16x32_bf16 v[104:107], v[160:163], v[192:195], v[104:107]
	v_mfma_f32_16x16x32_bf16 v[96:99], v[152:155], v[214:217], v[96:99]
	v_mfma_f32_16x16x32_bf16 v[88:91], v[160:163], v[214:217], v[88:91]
	v_mfma_f32_16x16x32_bf16 v[80:83], v[152:155], v[222:225], v[80:83]
	v_mfma_f32_16x16x32_bf16 v[72:75], v[160:163], v[222:225], v[72:75]
	s_setprio 0
	s_setprio 1
	v_mfma_f32_16x16x32_bf16 v[124:127], v[164:167], v[180:183], v[124:127]
	v_mfma_f32_16x16x32_bf16 v[116:119], v[172:175], v[180:183], v[116:119]
	v_mfma_f32_16x16x32_bf16 v[108:111], v[164:167], v[188:191], v[108:111]
	v_mfma_f32_16x16x32_bf16 v[100:103], v[172:175], v[188:191], v[100:103]
	v_mfma_f32_16x16x32_bf16 v[92:95], v[164:167], v[202:205], v[92:95]
	v_mfma_f32_16x16x32_bf16 v[84:87], v[172:175], v[202:205], v[84:87]
	v_mfma_f32_16x16x32_bf16 v[76:79], v[164:167], v[218:221], v[76:79]
	v_mfma_f32_16x16x32_bf16 v[68:71], v[172:175], v[218:221], v[68:71]
	v_mfma_f32_16x16x32_bf16 v[124:127], v[168:171], v[184:187], v[124:127]
	v_mfma_f32_16x16x32_bf16 v[116:119], v[176:179], v[184:187], v[116:119]
	v_mfma_f32_16x16x32_bf16 v[108:111], v[168:171], v[192:195], v[108:111]
	v_mfma_f32_16x16x32_bf16 v[100:103], v[176:179], v[192:195], v[100:103]
	v_mfma_f32_16x16x32_bf16 v[92:95], v[168:171], v[214:217], v[92:95]
	v_mfma_f32_16x16x32_bf16 v[84:87], v[176:179], v[214:217], v[84:87]
	v_mfma_f32_16x16x32_bf16 v[76:79], v[168:171], v[222:225], v[76:79]
	v_mfma_f32_16x16x32_bf16 v[68:71], v[176:179], v[222:225], v[68:71]
	s_setprio 0
	s_barrier
	s_add_i32 s61, s61, s46
	s_mov_b32 m0, s61
	ds_read_b128 v[180:183], v147 offset:16384
	ds_read_b128 v[184:187], v147 offset:17408
	ds_read_b128 v[188:191], v147 offset:18432
	ds_read_b128 v[192:195], v147 offset:19456
	ds_read_b128 v[202:205], v147 offset:20480
	ds_read_b128 v[214:217], v147 offset:21504
	ds_read_b128 v[218:221], v147 offset:22528
	ds_read_b128 v[222:225], v147 offset:23552
	global_load_lds_dwordx4 v2, s[40:41]
	s_add_i32 m0, s61, 0x2000
	s_add_u32 s62, s40, 0x4000
	s_addc_u32 s63, s41, 0
	s_add_i32 s61, s64, s46
	global_load_lds_dwordx4 v132, s[40:41]
	s_mov_b32 m0, s61
	v_lshl_add_u64 v[228:229], s[42:43], 0, v[134:135]
	global_load_lds_dwordx4 v2, s[62:63]
	s_add_i32 m0, s61, 0x2000
	s_nop 0
	global_load_lds_dwordx4 v132, s[62:63]
	v_lshl_add_u64 v[226:227], s[42:43], 0, v[136:137]
	s_mov_b32 m0, s47
	s_nop 0
	global_load_lds_dwordx4 v136, s[42:43]
	s_mov_b32 m0, s48
	s_nop 0
	global_load_lds_dwordx4 v134, s[42:43]
	s_waitcnt vmcnt(8)
	s_waitcnt lgkmcnt(0)
	s_barrier
	s_setprio 1
	s_waitcnt lgkmcnt(0)
	v_mfma_f32_16x16x32_bf16 v[64:67], v[148:151], v[180:183], v[64:67]
	v_mfma_f32_16x16x32_bf16 v[56:59], v[156:159], v[180:183], v[56:59]
	v_mfma_f32_16x16x32_bf16 v[48:51], v[148:151], v[188:191], v[48:51]
	v_mfma_f32_16x16x32_bf16 v[40:43], v[156:159], v[188:191], v[40:43]
	v_mfma_f32_16x16x32_bf16 v[32:35], v[148:151], v[202:205], v[32:35]
	v_mfma_f32_16x16x32_bf16 v[24:27], v[156:159], v[202:205], v[24:27]
	v_mfma_f32_16x16x32_bf16 v[16:19], v[148:151], v[218:221], v[16:19]
	v_mfma_f32_16x16x32_bf16 v[8:11], v[156:159], v[218:221], v[8:11]
	v_mfma_f32_16x16x32_bf16 v[64:67], v[152:155], v[184:187], v[64:67]
	v_mfma_f32_16x16x32_bf16 v[56:59], v[160:163], v[184:187], v[56:59]
	v_mfma_f32_16x16x32_bf16 v[48:51], v[152:155], v[192:195], v[48:51]
	v_mfma_f32_16x16x32_bf16 v[40:43], v[160:163], v[192:195], v[40:43]
	v_mfma_f32_16x16x32_bf16 v[32:35], v[152:155], v[214:217], v[32:35]
	v_mfma_f32_16x16x32_bf16 v[24:27], v[160:163], v[214:217], v[24:27]
	v_mfma_f32_16x16x32_bf16 v[16:19], v[152:155], v[222:225], v[16:19]
	v_mfma_f32_16x16x32_bf16 v[8:11], v[160:163], v[222:225], v[8:11]
	s_setprio 0
	s_setprio 1
	v_mfma_f32_16x16x32_bf16 v[60:63], v[164:167], v[180:183], v[60:63]
	v_mfma_f32_16x16x32_bf16 v[52:55], v[172:175], v[180:183], v[52:55]
	v_mfma_f32_16x16x32_bf16 v[44:47], v[164:167], v[188:191], v[44:47]
	v_mfma_f32_16x16x32_bf16 v[36:39], v[172:175], v[188:191], v[36:39]
	v_mfma_f32_16x16x32_bf16 v[28:31], v[164:167], v[202:205], v[28:31]
	v_mfma_f32_16x16x32_bf16 v[20:23], v[172:175], v[202:205], v[20:23]
	v_mfma_f32_16x16x32_bf16 v[12:15], v[164:167], v[218:221], v[12:15]
	v_mfma_f32_16x16x32_bf16 v[4:7], v[172:175], v[218:221], v[4:7]
	v_mfma_f32_16x16x32_bf16 v[60:63], v[168:171], v[184:187], v[60:63]
	v_mfma_f32_16x16x32_bf16 v[52:55], v[176:179], v[184:187], v[52:55]
	v_mfma_f32_16x16x32_bf16 v[44:47], v[168:171], v[192:195], v[44:47]
	v_mfma_f32_16x16x32_bf16 v[36:39], v[176:179], v[192:195], v[36:39]
	v_mfma_f32_16x16x32_bf16 v[28:31], v[168:171], v[214:217], v[28:31]
	v_mfma_f32_16x16x32_bf16 v[20:23], v[176:179], v[214:217], v[20:23]
	v_mfma_f32_16x16x32_bf16 v[12:15], v[168:171], v[222:225], v[12:15]
	v_mfma_f32_16x16x32_bf16 v[4:7], v[176:179], v[222:225], v[4:7]
	s_setprio 0
	s_barrier
	s_add_i32 s61, 0, 0x18000
	s_add_i32 s62, 0, 0x1c000
	v_add_u32_e32 v160, s61, v143
	v_add_u32_e32 v176, s62, v143
	ds_read_b128 v[148:151], v160
	ds_read_b128 v[152:155], v160 offset:1024
	ds_read_b128 v[156:159], v160 offset:2048
	ds_read_b128 v[160:163], v160 offset:3072
	ds_read_b128 v[164:167], v176
	ds_read_b128 v[168:171], v176 offset:1024
	ds_read_b128 v[172:175], v176 offset:2048
	ds_read_b128 v[176:179], v176 offset:3072
	s_add_u32 s42, s42, 0x80000
	s_addc_u32 s43, s43, 0
	s_mov_b32 m0, s49
	ds_read_b128 v[180:183], v147 offset:32768
	ds_read_b128 v[184:187], v147 offset:33792
	ds_read_b128 v[188:191], v147 offset:34816
	ds_read_b128 v[192:195], v147 offset:35840
	ds_read_b128 v[202:205], v147 offset:36864
	ds_read_b128 v[214:217], v147 offset:37888
	ds_read_b128 v[218:221], v147 offset:38912
	ds_read_b128 v[222:225], v147 offset:39936
	global_load_lds_dwordx4 v136, s[42:43]
	s_mov_b32 m0, s50
	s_nop 0
	global_load_lds_dwordx4 v134, s[42:43]
	s_waitcnt vmcnt(8)
	s_waitcnt lgkmcnt(0)
	s_barrier
	s_setprio 1
	s_waitcnt lgkmcnt(0)
	v_mfma_f32_16x16x32_bf16 v[128:131], v[148:151], v[180:183], v[128:131]
	v_mfma_f32_16x16x32_bf16 v[120:123], v[156:159], v[180:183], v[120:123]
	v_mfma_f32_16x16x32_bf16 v[112:115], v[148:151], v[188:191], v[112:115]
	v_mfma_f32_16x16x32_bf16 v[104:107], v[156:159], v[188:191], v[104:107]
	v_mfma_f32_16x16x32_bf16 v[96:99], v[148:151], v[202:205], v[96:99]
	v_mfma_f32_16x16x32_bf16 v[88:91], v[156:159], v[202:205], v[88:91]
	v_mfma_f32_16x16x32_bf16 v[80:83], v[148:151], v[218:221], v[80:83]
	v_mfma_f32_16x16x32_bf16 v[72:75], v[156:159], v[218:221], v[72:75]
	v_mfma_f32_16x16x32_bf16 v[128:131], v[152:155], v[184:187], v[128:131]
	v_mfma_f32_16x16x32_bf16 v[120:123], v[160:163], v[184:187], v[120:123]
	v_mfma_f32_16x16x32_bf16 v[112:115], v[152:155], v[192:195], v[112:115]
	v_mfma_f32_16x16x32_bf16 v[104:107], v[160:163], v[192:195], v[104:107]
	v_mfma_f32_16x16x32_bf16 v[96:99], v[152:155], v[214:217], v[96:99]
	v_mfma_f32_16x16x32_bf16 v[88:91], v[160:163], v[214:217], v[88:91]
	v_mfma_f32_16x16x32_bf16 v[80:83], v[152:155], v[222:225], v[80:83]
	v_mfma_f32_16x16x32_bf16 v[72:75], v[160:163], v[222:225], v[72:75]
	s_setprio 0
	s_setprio 1
	v_mfma_f32_16x16x32_bf16 v[124:127], v[164:167], v[180:183], v[124:127]
	v_mfma_f32_16x16x32_bf16 v[116:119], v[172:175], v[180:183], v[116:119]
	v_mfma_f32_16x16x32_bf16 v[108:111], v[164:167], v[188:191], v[108:111]
	v_mfma_f32_16x16x32_bf16 v[100:103], v[172:175], v[188:191], v[100:103]
	v_mfma_f32_16x16x32_bf16 v[92:95], v[164:167], v[202:205], v[92:95]
	v_mfma_f32_16x16x32_bf16 v[84:87], v[172:175], v[202:205], v[84:87]
	v_mfma_f32_16x16x32_bf16 v[76:79], v[164:167], v[218:221], v[76:79]
	v_mfma_f32_16x16x32_bf16 v[68:71], v[172:175], v[218:221], v[68:71]
	v_mfma_f32_16x16x32_bf16 v[124:127], v[168:171], v[184:187], v[124:127]
	v_mfma_f32_16x16x32_bf16 v[116:119], v[176:179], v[184:187], v[116:119]
	v_mfma_f32_16x16x32_bf16 v[108:111], v[168:171], v[192:195], v[108:111]
	v_mfma_f32_16x16x32_bf16 v[100:103], v[176:179], v[192:195], v[100:103]
	v_mfma_f32_16x16x32_bf16 v[92:95], v[168:171], v[214:217], v[92:95]
	v_mfma_f32_16x16x32_bf16 v[84:87], v[176:179], v[214:217], v[84:87]
	v_mfma_f32_16x16x32_bf16 v[76:79], v[168:171], v[222:225], v[76:79]
	v_mfma_f32_16x16x32_bf16 v[68:71], v[176:179], v[222:225], v[68:71]
	s_setprio 0
	s_barrier
	s_add_u32 s42, s40, 0x8000
	s_addc_u32 s43, s41, 0
	s_add_i32 s61, s61, s46
	s_mov_b32 m0, s61
	ds_read_b128 v[180:183], v147 offset:49152
	ds_read_b128 v[184:187], v147 offset:50176
	ds_read_b128 v[188:191], v147 offset:51200
	ds_read_b128 v[192:195], v147 offset:52224
	ds_read_b128 v[202:205], v147 offset:53248
	ds_read_b128 v[214:217], v147 offset:54272
	ds_read_b128 v[218:221], v147 offset:55296
	ds_read_b128 v[222:225], v147 offset:56320
	global_load_lds_dwordx4 v2, s[42:43]
	s_add_i32 m0, s61, 0x2000
	s_add_u32 s40, s40, 0xc000
	v_lshl_add_u64 v[230:231], s[42:43], 0, v[132:133]
	s_addc_u32 s41, s41, 0
	s_add_i32 s42, s62, s46
	global_load_lds_dwordx4 v[230:231], off
	s_mov_b32 m0, s42
	v_lshl_add_u64 v[226:227], v[226:227], 0, s[4:5]
	global_load_lds_dwordx4 v2, s[40:41]
	s_add_i32 m0, s42, 0x2000
	s_nop 0
	global_load_lds_dwordx4 v132, s[40:41]
	s_mov_b32 m0, s51
	s_nop 0
	global_load_lds_dwordx4 v[226:227], off
	v_lshl_add_u64 v[226:227], v[228:229], 0, s[4:5]
	s_mov_b32 m0, s52
	s_nop 0
	global_load_lds_dwordx4 v[226:227], off
	s_waitcnt vmcnt(8)
	s_waitcnt lgkmcnt(0)
	s_barrier
	s_setprio 1
	s_waitcnt lgkmcnt(0)
	v_mfma_f32_16x16x32_bf16 v[64:67], v[148:151], v[180:183], v[64:67]
	v_mfma_f32_16x16x32_bf16 v[56:59], v[156:159], v[180:183], v[56:59]
	v_mfma_f32_16x16x32_bf16 v[48:51], v[148:151], v[188:191], v[48:51]
	v_mfma_f32_16x16x32_bf16 v[40:43], v[156:159], v[188:191], v[40:43]
	v_mfma_f32_16x16x32_bf16 v[32:35], v[148:151], v[202:205], v[32:35]
	v_mfma_f32_16x16x32_bf16 v[24:27], v[156:159], v[202:205], v[24:27]
	v_mfma_f32_16x16x32_bf16 v[16:19], v[148:151], v[218:221], v[16:19]
	v_mfma_f32_16x16x32_bf16 v[8:11], v[156:159], v[218:221], v[8:11]
	v_mfma_f32_16x16x32_bf16 v[64:67], v[152:155], v[184:187], v[64:67]
	v_mfma_f32_16x16x32_bf16 v[56:59], v[160:163], v[184:187], v[56:59]
	v_mfma_f32_16x16x32_bf16 v[48:51], v[152:155], v[192:195], v[48:51]
	v_mfma_f32_16x16x32_bf16 v[40:43], v[160:163], v[192:195], v[40:43]
	v_mfma_f32_16x16x32_bf16 v[32:35], v[152:155], v[214:217], v[32:35]
	v_mfma_f32_16x16x32_bf16 v[24:27], v[160:163], v[214:217], v[24:27]
	v_mfma_f32_16x16x32_bf16 v[16:19], v[152:155], v[222:225], v[16:19]
	v_mfma_f32_16x16x32_bf16 v[8:11], v[160:163], v[222:225], v[8:11]
	s_setprio 0
	s_setprio 1
	v_mfma_f32_16x16x32_bf16 v[60:63], v[164:167], v[180:183], v[60:63]
	v_mfma_f32_16x16x32_bf16 v[52:55], v[172:175], v[180:183], v[52:55]
	v_mfma_f32_16x16x32_bf16 v[44:47], v[164:167], v[188:191], v[44:47]
	v_mfma_f32_16x16x32_bf16 v[36:39], v[172:175], v[188:191], v[36:39]
	v_mfma_f32_16x16x32_bf16 v[28:31], v[164:167], v[202:205], v[28:31]
	v_mfma_f32_16x16x32_bf16 v[20:23], v[172:175], v[202:205], v[20:23]
	v_mfma_f32_16x16x32_bf16 v[12:15], v[164:167], v[218:221], v[12:15]
	v_mfma_f32_16x16x32_bf16 v[4:7], v[172:175], v[218:221], v[4:7]
	v_mfma_f32_16x16x32_bf16 v[60:63], v[168:171], v[184:187], v[60:63]
	v_mfma_f32_16x16x32_bf16 v[52:55], v[176:179], v[184:187], v[52:55]
	v_mfma_f32_16x16x32_bf16 v[44:47], v[168:171], v[192:195], v[44:47]
	v_mfma_f32_16x16x32_bf16 v[36:39], v[176:179], v[192:195], v[36:39]
	v_mfma_f32_16x16x32_bf16 v[28:31], v[168:171], v[214:217], v[28:31]
	v_mfma_f32_16x16x32_bf16 v[20:23], v[176:179], v[214:217], v[20:23]
	v_mfma_f32_16x16x32_bf16 v[12:15], v[168:171], v[222:225], v[12:15]
	v_mfma_f32_16x16x32_bf16 v[4:7], v[176:179], v[222:225], v[4:7]
	s_setprio 0
	s_barrier
	s_add_i32 s60, s60, 2
	s_add_u32 s58, s58, 0x10000
	s_addc_u32 s59, s59, 0
	s_add_u32 s34, s34, 0x100
	s_addc_u32 s35, s35, 0
	s_cmp_gt_u32 s60, 29
	s_cbranch_scc0 .LBB0_146
	s_and_b64 vcc, exec, s[6:7]
	s_cbranch_vccz .LBB0_149
	s_barrier

.LBB0_223:
	s_add_u32 s22, s14, 0x100
	s_addc_u32 s23, s15, 0
	s_add_i32 s67, 0, 0x10000
	s_cmpk_eq_i32 s66, 0x54
	s_cselect_b32 s49, s9, s23
	s_cselect_b32 s48, s8, s22
	s_cselect_b32 s35, s13, s65
	s_cselect_b32 s34, s12, s64
	s_add_i32 s68, 0, 0x14000
	v_add_u32_e32 v136, s67, v202
	v_add_u32_e32 v156, s68, v202
	ds_read_b128 v[108:111], v136
	ds_read_b128 v[116:119], v136 offset:1024
	ds_read_b128 v[128:131], v136 offset:2048
	ds_read_b128 v[136:139], v136 offset:3072
	ds_read_b128 v[140:143], v156
	ds_read_b128 v[144:147], v156 offset:1024
	ds_read_b128 v[148:151], v156 offset:2048
	ds_read_b128 v[156:159], v156 offset:3072
	s_add_i32 m0, s53, 0xc000
	ds_read_b128 v[164:167], v204
	ds_read_b128 v[168:171], v204 offset:1024
	ds_read_b128 v[172:175], v204 offset:2048
	ds_read_b128 v[176:179], v204 offset:3072
	ds_read_b128 v[180:183], v204 offset:4096
	ds_read_b128 v[184:187], v204 offset:5120
	ds_read_b128 v[188:191], v204 offset:6144
	ds_read_b128 v[192:195], v204 offset:7168
	global_load_lds_dwordx4 v220, s[14:15]
	s_add_i32 m0, s53, 0xe000
	s_nop 0
	global_load_lds_dwordx4 v222, s[14:15]
	s_waitcnt vmcnt(8)
	s_waitcnt lgkmcnt(0)
	s_barrier
	s_setprio 1
	s_waitcnt lgkmcnt(0)
	v_mfma_f32_16x16x32_bf16 v[160:163], v[108:111], v[164:167], v[160:163]
	v_mfma_f32_16x16x32_bf16 v[152:155], v[128:131], v[164:167], v[152:155]
	v_mfma_f32_16x16x32_bf16 v[120:123], v[108:111], v[172:175], v[120:123]
	v_mfma_f32_16x16x32_bf16 v[112:115], v[128:131], v[172:175], v[112:115]
	v_mfma_f32_16x16x32_bf16 v[96:99], v[108:111], v[180:183], v[96:99]
	v_mfma_f32_16x16x32_bf16 v[92:95], v[128:131], v[180:183], v[92:95]
	v_mfma_f32_16x16x32_bf16 v[80:83], v[108:111], v[188:191], v[80:83]
	v_mfma_f32_16x16x32_bf16 v[76:79], v[128:131], v[188:191], v[76:79]
	v_mfma_f32_16x16x32_bf16 v[160:163], v[116:119], v[168:171], v[160:163]
	v_mfma_f32_16x16x32_bf16 v[152:155], v[136:139], v[168:171], v[152:155]
	v_mfma_f32_16x16x32_bf16 v[120:123], v[116:119], v[176:179], v[120:123]
	v_mfma_f32_16x16x32_bf16 v[112:115], v[136:139], v[176:179], v[112:115]
	v_mfma_f32_16x16x32_bf16 v[96:99], v[116:119], v[184:187], v[96:99]
	v_mfma_f32_16x16x32_bf16 v[92:95], v[136:139], v[184:187], v[92:95]
	v_mfma_f32_16x16x32_bf16 v[80:83], v[116:119], v[192:195], v[80:83]
	v_mfma_f32_16x16x32_bf16 v[76:79], v[136:139], v[192:195], v[76:79]
	s_setprio 0
	s_setprio 1
	v_mfma_f32_16x16x32_bf16 v[132:135], v[140:143], v[164:167], v[132:135]
	v_mfma_f32_16x16x32_bf16 v[124:127], v[148:151], v[164:167], v[124:127]
	v_mfma_f32_16x16x32_bf16 v[104:107], v[140:143], v[172:175], v[104:107]
	v_mfma_f32_16x16x32_bf16 v[100:103], v[148:151], v[172:175], v[100:103]
	v_mfma_f32_16x16x32_bf16 v[88:91], v[140:143], v[180:183], v[88:91]
	v_mfma_f32_16x16x32_bf16 v[84:87], v[148:151], v[180:183], v[84:87]
	v_mfma_f32_16x16x32_bf16 v[72:75], v[140:143], v[188:191], v[72:75]
	v_mfma_f32_16x16x32_bf16 v[68:71], v[148:151], v[188:191], v[68:71]
	v_mfma_f32_16x16x32_bf16 v[132:135], v[144:147], v[168:171], v[132:135]
	v_mfma_f32_16x16x32_bf16 v[124:127], v[156:159], v[168:171], v[124:127]
	v_mfma_f32_16x16x32_bf16 v[104:107], v[144:147], v[176:179], v[104:107]
	v_mfma_f32_16x16x32_bf16 v[100:103], v[156:159], v[176:179], v[100:103]
	v_mfma_f32_16x16x32_bf16 v[88:91], v[144:147], v[184:187], v[88:91]
	v_mfma_f32_16x16x32_bf16 v[84:87], v[156:159], v[184:187], v[84:87]
	v_mfma_f32_16x16x32_bf16 v[72:75], v[144:147], v[192:195], v[72:75]
	v_mfma_f32_16x16x32_bf16 v[68:71], v[156:159], v[192:195], v[68:71]
	s_setprio 0
	s_barrier
	s_add_i32 s14, s67, s52
	s_mov_b32 m0, s14
	ds_read_b128 v[164:167], v204 offset:16384
	ds_read_b128 v[168:171], v204 offset:17408
	ds_read_b128 v[172:175], v204 offset:18432
	ds_read_b128 v[176:179], v204 offset:19456
	ds_read_b128 v[180:183], v204 offset:20480
	ds_read_b128 v[184:187], v204 offset:21504
	ds_read_b128 v[188:191], v204 offset:22528
	ds_read_b128 v[192:195], v204 offset:23552
	global_load_lds_dwordx4 v2, s[34:35]
	s_add_i32 m0, s14, 0x2000
	s_add_u32 s14, s34, 0x4000
	s_addc_u32 s15, s35, 0
	s_add_i32 s67, s68, s52
	global_load_lds_dwordx4 v214, s[34:35]
	s_mov_b32 m0, s67
	v_lshl_add_u64 v[226:227], s[48:49], 0, v[216:217]
	global_load_lds_dwordx4 v2, s[14:15]
	s_add_i32 m0, s67, 0x2000
	s_nop 0
	global_load_lds_dwordx4 v214, s[14:15]
	v_lshl_add_u64 v[224:225], s[48:49], 0, v[218:219]
	s_mov_b32 m0, s53
	s_nop 0
	global_load_lds_dwordx4 v218, s[48:49]
	s_mov_b32 m0, s54
	s_nop 0
	global_load_lds_dwordx4 v216, s[48:49]
	s_waitcnt vmcnt(8)
	s_waitcnt lgkmcnt(0)
	s_barrier
	s_setprio 1
	s_waitcnt lgkmcnt(0)
	v_mfma_f32_16x16x32_bf16 v[64:67], v[108:111], v[164:167], v[64:67]
	v_mfma_f32_16x16x32_bf16 v[60:63], v[128:131], v[164:167], v[60:63]
	v_mfma_f32_16x16x32_bf16 v[48:51], v[108:111], v[172:175], v[48:51]
	v_mfma_f32_16x16x32_bf16 v[44:47], v[128:131], v[172:175], v[44:47]
	v_mfma_f32_16x16x32_bf16 v[32:35], v[108:111], v[180:183], v[32:35]
	v_mfma_f32_16x16x32_bf16 v[28:31], v[128:131], v[180:183], v[28:31]
	v_mfma_f32_16x16x32_bf16 v[16:19], v[108:111], v[188:191], v[16:19]
	v_mfma_f32_16x16x32_bf16 v[12:15], v[128:131], v[188:191], v[12:15]
	v_mfma_f32_16x16x32_bf16 v[64:67], v[116:119], v[168:171], v[64:67]
	v_mfma_f32_16x16x32_bf16 v[60:63], v[136:139], v[168:171], v[60:63]
	v_mfma_f32_16x16x32_bf16 v[48:51], v[116:119], v[176:179], v[48:51]
	v_mfma_f32_16x16x32_bf16 v[44:47], v[136:139], v[176:179], v[44:47]
	v_mfma_f32_16x16x32_bf16 v[32:35], v[116:119], v[184:187], v[32:35]
	v_mfma_f32_16x16x32_bf16 v[28:31], v[136:139], v[184:187], v[28:31]
	v_mfma_f32_16x16x32_bf16 v[16:19], v[116:119], v[192:195], v[16:19]
	v_mfma_f32_16x16x32_bf16 v[12:15], v[136:139], v[192:195], v[12:15]
	s_setprio 0
	s_setprio 1
	v_mfma_f32_16x16x32_bf16 v[56:59], v[140:143], v[164:167], v[56:59]
	v_mfma_f32_16x16x32_bf16 v[52:55], v[148:151], v[164:167], v[52:55]
	v_mfma_f32_16x16x32_bf16 v[40:43], v[140:143], v[172:175], v[40:43]
	v_mfma_f32_16x16x32_bf16 v[36:39], v[148:151], v[172:175], v[36:39]
	v_mfma_f32_16x16x32_bf16 v[24:27], v[140:143], v[180:183], v[24:27]
	v_mfma_f32_16x16x32_bf16 v[20:23], v[148:151], v[180:183], v[20:23]
	v_mfma_f32_16x16x32_bf16 v[8:11], v[140:143], v[188:191], v[8:11]
	v_mfma_f32_16x16x32_bf16 v[4:7], v[148:151], v[188:191], v[4:7]
	v_mfma_f32_16x16x32_bf16 v[56:59], v[144:147], v[168:171], v[56:59]
	v_mfma_f32_16x16x32_bf16 v[52:55], v[156:159], v[168:171], v[52:55]
	v_mfma_f32_16x16x32_bf16 v[40:43], v[144:147], v[176:179], v[40:43]
	v_mfma_f32_16x16x32_bf16 v[36:39], v[156:159], v[176:179], v[36:39]
	v_mfma_f32_16x16x32_bf16 v[24:27], v[144:147], v[184:187], v[24:27]
	v_mfma_f32_16x16x32_bf16 v[20:23], v[156:159], v[184:187], v[20:23]
	v_mfma_f32_16x16x32_bf16 v[8:11], v[144:147], v[192:195], v[8:11]
	v_mfma_f32_16x16x32_bf16 v[4:7], v[156:159], v[192:195], v[4:7]
	s_setprio 0
	s_barrier
	s_add_i32 s67, 0, 0x18000
	s_add_i32 s68, 0, 0x1c000
	v_add_u32_e32 v136, s67, v202
	v_add_u32_e32 v156, s68, v202
	ds_read_b128 v[108:111], v136
	ds_read_b128 v[116:119], v136 offset:1024
	ds_read_b128 v[128:131], v136 offset:2048
	ds_read_b128 v[136:139], v136 offset:3072
	ds_read_b128 v[140:143], v156
	ds_read_b128 v[144:147], v156 offset:1024
	ds_read_b128 v[148:151], v156 offset:2048
	ds_read_b128 v[156:159], v156 offset:3072
	s_add_u32 s14, s48, 0x160000
	s_addc_u32 s15, s49, 0
	s_mov_b32 m0, s55
	ds_read_b128 v[164:167], v204 offset:32768
	ds_read_b128 v[168:171], v204 offset:33792
	ds_read_b128 v[172:175], v204 offset:34816
	ds_read_b128 v[176:179], v204 offset:35840
	ds_read_b128 v[180:183], v204 offset:36864
	ds_read_b128 v[184:187], v204 offset:37888
	ds_read_b128 v[188:191], v204 offset:38912
	ds_read_b128 v[192:195], v204 offset:39936
	global_load_lds_dwordx4 v218, s[14:15]
	s_mov_b32 m0, s56
	s_nop 0
	global_load_lds_dwordx4 v216, s[14:15]
	s_waitcnt vmcnt(8)
	s_waitcnt lgkmcnt(0)
	s_barrier
	s_setprio 1
	s_waitcnt lgkmcnt(0)
	v_mfma_f32_16x16x32_bf16 v[160:163], v[108:111], v[164:167], v[160:163]
	v_mfma_f32_16x16x32_bf16 v[152:155], v[128:131], v[164:167], v[152:155]
	v_mfma_f32_16x16x32_bf16 v[120:123], v[108:111], v[172:175], v[120:123]
	v_mfma_f32_16x16x32_bf16 v[112:115], v[128:131], v[172:175], v[112:115]
	v_mfma_f32_16x16x32_bf16 v[96:99], v[108:111], v[180:183], v[96:99]
	v_mfma_f32_16x16x32_bf16 v[92:95], v[128:131], v[180:183], v[92:95]
	v_mfma_f32_16x16x32_bf16 v[80:83], v[108:111], v[188:191], v[80:83]
	v_mfma_f32_16x16x32_bf16 v[76:79], v[128:131], v[188:191], v[76:79]
	v_mfma_f32_16x16x32_bf16 v[160:163], v[116:119], v[168:171], v[160:163]
	v_mfma_f32_16x16x32_bf16 v[152:155], v[136:139], v[168:171], v[152:155]
	v_mfma_f32_16x16x32_bf16 v[120:123], v[116:119], v[176:179], v[120:123]
	v_mfma_f32_16x16x32_bf16 v[112:115], v[136:139], v[176:179], v[112:115]
	v_mfma_f32_16x16x32_bf16 v[96:99], v[116:119], v[184:187], v[96:99]
	v_mfma_f32_16x16x32_bf16 v[92:95], v[136:139], v[184:187], v[92:95]
	v_mfma_f32_16x16x32_bf16 v[80:83], v[116:119], v[192:195], v[80:83]
	v_mfma_f32_16x16x32_bf16 v[76:79], v[136:139], v[192:195], v[76:79]
	s_setprio 0
	s_setprio 1
	v_mfma_f32_16x16x32_bf16 v[132:135], v[140:143], v[164:167], v[132:135]
	v_mfma_f32_16x16x32_bf16 v[124:127], v[148:151], v[164:167], v[124:127]
	v_mfma_f32_16x16x32_bf16 v[104:107], v[140:143], v[172:175], v[104:107]
	v_mfma_f32_16x16x32_bf16 v[100:103], v[148:151], v[172:175], v[100:103]
	v_mfma_f32_16x16x32_bf16 v[88:91], v[140:143], v[180:183], v[88:91]
	v_mfma_f32_16x16x32_bf16 v[84:87], v[148:151], v[180:183], v[84:87]
	v_mfma_f32_16x16x32_bf16 v[72:75], v[140:143], v[188:191], v[72:75]
	v_mfma_f32_16x16x32_bf16 v[68:71], v[148:151], v[188:191], v[68:71]
	v_mfma_f32_16x16x32_bf16 v[132:135], v[144:147], v[168:171], v[132:135]
	v_mfma_f32_16x16x32_bf16 v[124:127], v[156:159], v[168:171], v[124:127]
	v_mfma_f32_16x16x32_bf16 v[104:107], v[144:147], v[176:179], v[104:107]
	v_mfma_f32_16x16x32_bf16 v[100:103], v[156:159], v[176:179], v[100:103]
	v_mfma_f32_16x16x32_bf16 v[88:91], v[144:147], v[184:187], v[88:91]
	v_mfma_f32_16x16x32_bf16 v[84:87], v[156:159], v[184:187], v[84:87]
	v_mfma_f32_16x16x32_bf16 v[72:75], v[144:147], v[192:195], v[72:75]
	v_mfma_f32_16x16x32_bf16 v[68:71], v[156:159], v[192:195], v[68:71]
	s_setprio 0
	s_barrier
	s_add_u32 s14, s34, 0x8000
	s_addc_u32 s15, s35, 0
	s_add_i32 s48, s67, s52
	s_mov_b32 m0, s48
	ds_read_b128 v[164:167], v204 offset:49152
	ds_read_b128 v[168:171], v204 offset:50176
	ds_read_b128 v[172:175], v204 offset:51200
	ds_read_b128 v[176:179], v204 offset:52224
	ds_read_b128 v[180:183], v204 offset:53248
	ds_read_b128 v[184:187], v204 offset:54272
	ds_read_b128 v[188:191], v204 offset:55296
	ds_read_b128 v[192:195], v204 offset:56320
	global_load_lds_dwordx4 v2, s[14:15]
	s_add_i32 m0, s48, 0x2000
	v_lshl_add_u64 v[228:229], s[14:15], 0, v[214:215]
	s_add_u32 s14, s34, 0xc000
	s_addc_u32 s15, s35, 0
	s_add_i32 s34, s68, s52
	global_load_lds_dwordx4 v[228:229], off
	s_mov_b32 m0, s34
	v_lshl_add_u64 v[224:225], v[224:225], 0, s[4:5]
	global_load_lds_dwordx4 v2, s[14:15]
	s_add_i32 m0, s34, 0x2000
	s_nop 0
	global_load_lds_dwordx4 v214, s[14:15]
	s_mov_b32 m0, s57
	s_nop 0
	global_load_lds_dwordx4 v[224:225], off
	v_lshl_add_u64 v[224:225], v[226:227], 0, s[4:5]
	s_mov_b32 m0, s58
	s_nop 0
	global_load_lds_dwordx4 v[224:225], off
	s_waitcnt vmcnt(8)
	s_waitcnt lgkmcnt(0)
	s_barrier
	s_setprio 1
	s_waitcnt lgkmcnt(0)
	v_mfma_f32_16x16x32_bf16 v[64:67], v[108:111], v[164:167], v[64:67]
	v_mfma_f32_16x16x32_bf16 v[60:63], v[128:131], v[164:167], v[60:63]
	v_mfma_f32_16x16x32_bf16 v[48:51], v[108:111], v[172:175], v[48:51]
	v_mfma_f32_16x16x32_bf16 v[44:47], v[128:131], v[172:175], v[44:47]
	v_mfma_f32_16x16x32_bf16 v[32:35], v[108:111], v[180:183], v[32:35]
	v_mfma_f32_16x16x32_bf16 v[28:31], v[128:131], v[180:183], v[28:31]
	v_mfma_f32_16x16x32_bf16 v[16:19], v[108:111], v[188:191], v[16:19]
	v_mfma_f32_16x16x32_bf16 v[12:15], v[128:131], v[188:191], v[12:15]
	v_mfma_f32_16x16x32_bf16 v[64:67], v[116:119], v[168:171], v[64:67]
	v_mfma_f32_16x16x32_bf16 v[60:63], v[136:139], v[168:171], v[60:63]
	v_mfma_f32_16x16x32_bf16 v[48:51], v[116:119], v[176:179], v[48:51]
	v_mfma_f32_16x16x32_bf16 v[44:47], v[136:139], v[176:179], v[44:47]
	v_mfma_f32_16x16x32_bf16 v[32:35], v[116:119], v[184:187], v[32:35]
	v_mfma_f32_16x16x32_bf16 v[28:31], v[136:139], v[184:187], v[28:31]
	v_mfma_f32_16x16x32_bf16 v[16:19], v[116:119], v[192:195], v[16:19]
	v_mfma_f32_16x16x32_bf16 v[12:15], v[136:139], v[192:195], v[12:15]
	s_setprio 0
	s_setprio 1
	v_mfma_f32_16x16x32_bf16 v[56:59], v[140:143], v[164:167], v[56:59]
	v_mfma_f32_16x16x32_bf16 v[52:55], v[148:151], v[164:167], v[52:55]
	v_mfma_f32_16x16x32_bf16 v[40:43], v[140:143], v[172:175], v[40:43]
	v_mfma_f32_16x16x32_bf16 v[36:39], v[148:151], v[172:175], v[36:39]
	v_mfma_f32_16x16x32_bf16 v[24:27], v[140:143], v[180:183], v[24:27]
	v_mfma_f32_16x16x32_bf16 v[20:23], v[148:151], v[180:183], v[20:23]
	v_mfma_f32_16x16x32_bf16 v[8:11], v[140:143], v[188:191], v[8:11]
	v_mfma_f32_16x16x32_bf16 v[4:7], v[148:151], v[188:191], v[4:7]
	v_mfma_f32_16x16x32_bf16 v[56:59], v[144:147], v[168:171], v[56:59]
	v_mfma_f32_16x16x32_bf16 v[52:55], v[156:159], v[168:171], v[52:55]
	v_mfma_f32_16x16x32_bf16 v[40:43], v[144:147], v[176:179], v[40:43]
	v_mfma_f32_16x16x32_bf16 v[36:39], v[156:159], v[176:179], v[36:39]
	v_mfma_f32_16x16x32_bf16 v[24:27], v[144:147], v[184:187], v[24:27]
	v_mfma_f32_16x16x32_bf16 v[20:23], v[156:159], v[184:187], v[20:23]
	v_mfma_f32_16x16x32_bf16 v[8:11], v[144:147], v[192:195], v[8:11]
	v_mfma_f32_16x16x32_bf16 v[4:7], v[156:159], v[192:195], v[4:7]
	s_setprio 0
	s_barrier
	s_add_i32 s66, s66, 2
	s_add_u32 s64, s64, 0x10000
	s_addc_u32 s65, s65, 0
	s_cmpk_gt_u32 s66, 0x55
	s_mov_b64 s[14:15], s[22:23]
	s_cbranch_scc0 .LBB0_223
	s_and_b64 vcc, exec, s[6:7]
	s_cbranch_vccz .LBB0_226
	s_barrier

.LBB0_326:
	s_add_u32 s40, s34, 0xfff80080
	s_addc_u32 s41, s35, -1
	s_add_i32 s59, 0, 0x10000
	s_cmp_eq_u32 s58, 28
	s_cselect_b32 s43, s13, s41
	s_cselect_b32 s42, s54, s40
	s_cselect_b32 s41, s9, s57
	s_cselect_b32 s40, s55, s56
	s_add_i32 s62, 0, 0x14000
	v_add_u32_e32 v160, s59, v147
	v_add_u32_e32 v176, s62, v147
	ds_read_b128 v[142:145], v160
	ds_read_b128 v[152:155], v160 offset:1024
	ds_read_b128 v[156:159], v160 offset:2048
	ds_read_b128 v[160:163], v160 offset:3072
	ds_read_b128 v[164:167], v176
	ds_read_b128 v[168:171], v176 offset:1024
	ds_read_b128 v[172:175], v176 offset:2048
	ds_read_b128 v[176:179], v176 offset:3072
	s_add_i32 m0, s45, 0xc000
	ds_read_b128 v[180:183], v151
	ds_read_b128 v[184:187], v151 offset:1024
	ds_read_b128 v[188:191], v151 offset:2048
	ds_read_b128 v[192:195], v151 offset:3072
	ds_read_b128 v[202:205], v151 offset:4096
	ds_read_b128 v[214:217], v151 offset:5120
	ds_read_b128 v[218:221], v151 offset:6144
	ds_read_b128 v[222:225], v151 offset:7168
	global_load_lds_dwordx4 v138, s[34:35]
	s_add_i32 m0, s45, 0xe000
	s_nop 0
	global_load_lds_dwordx4 v140, s[34:35]
	s_waitcnt vmcnt(8)
	s_waitcnt lgkmcnt(0)
	s_barrier
	s_setprio 1
	s_waitcnt lgkmcnt(0)
	v_mfma_f32_16x16x32_bf16 v[128:131], v[142:145], v[180:183], v[128:131]
	v_mfma_f32_16x16x32_bf16 v[124:127], v[156:159], v[180:183], v[124:127]
	v_mfma_f32_16x16x32_bf16 v[112:115], v[142:145], v[188:191], v[112:115]
	v_mfma_f32_16x16x32_bf16 v[108:111], v[156:159], v[188:191], v[108:111]
	v_mfma_f32_16x16x32_bf16 v[96:99], v[142:145], v[202:205], v[96:99]
	v_mfma_f32_16x16x32_bf16 v[92:95], v[156:159], v[202:205], v[92:95]
	v_mfma_f32_16x16x32_bf16 v[80:83], v[142:145], v[218:221], v[80:83]
	v_mfma_f32_16x16x32_bf16 v[76:79], v[156:159], v[218:221], v[76:79]
	v_mfma_f32_16x16x32_bf16 v[128:131], v[152:155], v[184:187], v[128:131]
	v_mfma_f32_16x16x32_bf16 v[124:127], v[160:163], v[184:187], v[124:127]
	v_mfma_f32_16x16x32_bf16 v[112:115], v[152:155], v[192:195], v[112:115]
	v_mfma_f32_16x16x32_bf16 v[108:111], v[160:163], v[192:195], v[108:111]
	v_mfma_f32_16x16x32_bf16 v[96:99], v[152:155], v[214:217], v[96:99]
	v_mfma_f32_16x16x32_bf16 v[92:95], v[160:163], v[214:217], v[92:95]
	v_mfma_f32_16x16x32_bf16 v[80:83], v[152:155], v[222:225], v[80:83]
	v_mfma_f32_16x16x32_bf16 v[76:79], v[160:163], v[222:225], v[76:79]
	s_setprio 0
	s_setprio 1
	v_mfma_f32_16x16x32_bf16 v[120:123], v[164:167], v[180:183], v[120:123]
	v_mfma_f32_16x16x32_bf16 v[116:119], v[172:175], v[180:183], v[116:119]
	v_mfma_f32_16x16x32_bf16 v[104:107], v[164:167], v[188:191], v[104:107]
	v_mfma_f32_16x16x32_bf16 v[100:103], v[172:175], v[188:191], v[100:103]
	v_mfma_f32_16x16x32_bf16 v[88:91], v[164:167], v[202:205], v[88:91]
	v_mfma_f32_16x16x32_bf16 v[84:87], v[172:175], v[202:205], v[84:87]
	v_mfma_f32_16x16x32_bf16 v[72:75], v[164:167], v[218:221], v[72:75]
	v_mfma_f32_16x16x32_bf16 v[68:71], v[172:175], v[218:221], v[68:71]
	v_mfma_f32_16x16x32_bf16 v[120:123], v[168:171], v[184:187], v[120:123]
	v_mfma_f32_16x16x32_bf16 v[116:119], v[176:179], v[184:187], v[116:119]
	v_mfma_f32_16x16x32_bf16 v[104:107], v[168:171], v[192:195], v[104:107]
	v_mfma_f32_16x16x32_bf16 v[100:103], v[176:179], v[192:195], v[100:103]
	v_mfma_f32_16x16x32_bf16 v[88:91], v[168:171], v[214:217], v[88:91]
	v_mfma_f32_16x16x32_bf16 v[84:87], v[176:179], v[214:217], v[84:87]
	v_mfma_f32_16x16x32_bf16 v[72:75], v[168:171], v[222:225], v[72:75]
	v_mfma_f32_16x16x32_bf16 v[68:71], v[176:179], v[222:225], v[68:71]
	s_setprio 0
	s_barrier
	s_add_i32 s59, s59, s44
	s_mov_b32 m0, s59
	ds_read_b128 v[180:183], v151 offset:16384
	ds_read_b128 v[184:187], v151 offset:17408
	ds_read_b128 v[188:191], v151 offset:18432
	ds_read_b128 v[192:195], v151 offset:19456
	ds_read_b128 v[202:205], v151 offset:20480
	ds_read_b128 v[214:217], v151 offset:21504
	ds_read_b128 v[218:221], v151 offset:22528
	ds_read_b128 v[222:225], v151 offset:23552
	global_load_lds_dwordx4 v2, s[40:41]
	s_add_i32 m0, s59, 0x2000
	s_add_u32 s60, s40, 0x4000
	s_addc_u32 s61, s41, 0
	s_add_i32 s59, s62, s44
	global_load_lds_dwordx4 v132, s[40:41]
	s_mov_b32 m0, s59
	v_lshl_add_u64 v[228:229], s[42:43], 0, v[134:135]
	global_load_lds_dwordx4 v2, s[60:61]
	s_add_i32 m0, s59, 0x2000
	s_nop 0
	global_load_lds_dwordx4 v132, s[60:61]
	v_lshl_add_u64 v[226:227], s[42:43], 0, v[136:137]
	s_mov_b32 m0, s45
	s_nop 0
	global_load_lds_dwordx4 v136, s[42:43]
	s_mov_b32 m0, s46
	s_nop 0
	global_load_lds_dwordx4 v134, s[42:43]
	s_waitcnt vmcnt(8)
	s_waitcnt lgkmcnt(0)
	s_barrier
	s_setprio 1
	s_waitcnt lgkmcnt(0)
	v_mfma_f32_16x16x32_bf16 v[64:67], v[142:145], v[180:183], v[64:67]
	v_mfma_f32_16x16x32_bf16 v[60:63], v[156:159], v[180:183], v[60:63]
	v_mfma_f32_16x16x32_bf16 v[48:51], v[142:145], v[188:191], v[48:51]
	v_mfma_f32_16x16x32_bf16 v[44:47], v[156:159], v[188:191], v[44:47]
	v_mfma_f32_16x16x32_bf16 v[32:35], v[142:145], v[202:205], v[32:35]
	v_mfma_f32_16x16x32_bf16 v[28:31], v[156:159], v[202:205], v[28:31]
	v_mfma_f32_16x16x32_bf16 v[16:19], v[142:145], v[218:221], v[16:19]
	v_mfma_f32_16x16x32_bf16 v[12:15], v[156:159], v[218:221], v[12:15]
	v_mfma_f32_16x16x32_bf16 v[64:67], v[152:155], v[184:187], v[64:67]
	v_mfma_f32_16x16x32_bf16 v[60:63], v[160:163], v[184:187], v[60:63]
	v_mfma_f32_16x16x32_bf16 v[48:51], v[152:155], v[192:195], v[48:51]
	v_mfma_f32_16x16x32_bf16 v[44:47], v[160:163], v[192:195], v[44:47]
	v_mfma_f32_16x16x32_bf16 v[32:35], v[152:155], v[214:217], v[32:35]
	v_mfma_f32_16x16x32_bf16 v[28:31], v[160:163], v[214:217], v[28:31]
	v_mfma_f32_16x16x32_bf16 v[16:19], v[152:155], v[222:225], v[16:19]
	v_mfma_f32_16x16x32_bf16 v[12:15], v[160:163], v[222:225], v[12:15]
	s_setprio 0
	s_setprio 1
	v_mfma_f32_16x16x32_bf16 v[56:59], v[164:167], v[180:183], v[56:59]
	v_mfma_f32_16x16x32_bf16 v[52:55], v[172:175], v[180:183], v[52:55]
	v_mfma_f32_16x16x32_bf16 v[40:43], v[164:167], v[188:191], v[40:43]
	v_mfma_f32_16x16x32_bf16 v[36:39], v[172:175], v[188:191], v[36:39]
	v_mfma_f32_16x16x32_bf16 v[24:27], v[164:167], v[202:205], v[24:27]
	v_mfma_f32_16x16x32_bf16 v[20:23], v[172:175], v[202:205], v[20:23]
	v_mfma_f32_16x16x32_bf16 v[8:11], v[164:167], v[218:221], v[8:11]
	v_mfma_f32_16x16x32_bf16 v[4:7], v[172:175], v[218:221], v[4:7]
	v_mfma_f32_16x16x32_bf16 v[56:59], v[168:171], v[184:187], v[56:59]
	v_mfma_f32_16x16x32_bf16 v[52:55], v[176:179], v[184:187], v[52:55]
	v_mfma_f32_16x16x32_bf16 v[40:43], v[168:171], v[192:195], v[40:43]
	v_mfma_f32_16x16x32_bf16 v[36:39], v[176:179], v[192:195], v[36:39]
	v_mfma_f32_16x16x32_bf16 v[24:27], v[168:171], v[214:217], v[24:27]
	v_mfma_f32_16x16x32_bf16 v[20:23], v[176:179], v[214:217], v[20:23]
	v_mfma_f32_16x16x32_bf16 v[8:11], v[168:171], v[222:225], v[8:11]
	v_mfma_f32_16x16x32_bf16 v[4:7], v[176:179], v[222:225], v[4:7]
	s_setprio 0
	s_barrier
	s_add_i32 s59, 0, 0x18000
	s_add_i32 s60, 0, 0x1c000
	v_add_u32_e32 v160, s59, v147
	v_add_u32_e32 v176, s60, v147
	ds_read_b128 v[142:145], v160
	ds_read_b128 v[152:155], v160 offset:1024
	ds_read_b128 v[156:159], v160 offset:2048
	ds_read_b128 v[160:163], v160 offset:3072
	ds_read_b128 v[164:167], v176
	ds_read_b128 v[168:171], v176 offset:1024
	ds_read_b128 v[172:175], v176 offset:2048
	ds_read_b128 v[176:179], v176 offset:3072
	s_add_u32 s42, s42, 0x80000
	s_addc_u32 s43, s43, 0
	s_mov_b32 m0, s47
	ds_read_b128 v[180:183], v151 offset:32768
	ds_read_b128 v[184:187], v151 offset:33792
	ds_read_b128 v[188:191], v151 offset:34816
	ds_read_b128 v[192:195], v151 offset:35840
	ds_read_b128 v[202:205], v151 offset:36864
	ds_read_b128 v[214:217], v151 offset:37888
	ds_read_b128 v[218:221], v151 offset:38912
	ds_read_b128 v[222:225], v151 offset:39936
	global_load_lds_dwordx4 v136, s[42:43]
	s_mov_b32 m0, s48
	s_nop 0
	global_load_lds_dwordx4 v134, s[42:43]
	s_waitcnt vmcnt(8)
	s_waitcnt lgkmcnt(0)
	s_barrier
	s_setprio 1
	s_waitcnt lgkmcnt(0)
	v_mfma_f32_16x16x32_bf16 v[128:131], v[142:145], v[180:183], v[128:131]
	v_mfma_f32_16x16x32_bf16 v[124:127], v[156:159], v[180:183], v[124:127]
	v_mfma_f32_16x16x32_bf16 v[112:115], v[142:145], v[188:191], v[112:115]
	v_mfma_f32_16x16x32_bf16 v[108:111], v[156:159], v[188:191], v[108:111]
	v_mfma_f32_16x16x32_bf16 v[96:99], v[142:145], v[202:205], v[96:99]
	v_mfma_f32_16x16x32_bf16 v[92:95], v[156:159], v[202:205], v[92:95]
	v_mfma_f32_16x16x32_bf16 v[80:83], v[142:145], v[218:221], v[80:83]
	v_mfma_f32_16x16x32_bf16 v[76:79], v[156:159], v[218:221], v[76:79]
	v_mfma_f32_16x16x32_bf16 v[128:131], v[152:155], v[184:187], v[128:131]
	v_mfma_f32_16x16x32_bf16 v[124:127], v[160:163], v[184:187], v[124:127]
	v_mfma_f32_16x16x32_bf16 v[112:115], v[152:155], v[192:195], v[112:115]
	v_mfma_f32_16x16x32_bf16 v[108:111], v[160:163], v[192:195], v[108:111]
	v_mfma_f32_16x16x32_bf16 v[96:99], v[152:155], v[214:217], v[96:99]
	v_mfma_f32_16x16x32_bf16 v[92:95], v[160:163], v[214:217], v[92:95]
	v_mfma_f32_16x16x32_bf16 v[80:83], v[152:155], v[222:225], v[80:83]
	v_mfma_f32_16x16x32_bf16 v[76:79], v[160:163], v[222:225], v[76:79]
	s_setprio 0
	s_setprio 1
	v_mfma_f32_16x16x32_bf16 v[120:123], v[164:167], v[180:183], v[120:123]
	v_mfma_f32_16x16x32_bf16 v[116:119], v[172:175], v[180:183], v[116:119]
	v_mfma_f32_16x16x32_bf16 v[104:107], v[164:167], v[188:191], v[104:107]
	v_mfma_f32_16x16x32_bf16 v[100:103], v[172:175], v[188:191], v[100:103]
	v_mfma_f32_16x16x32_bf16 v[88:91], v[164:167], v[202:205], v[88:91]
	v_mfma_f32_16x16x32_bf16 v[84:87], v[172:175], v[202:205], v[84:87]
	v_mfma_f32_16x16x32_bf16 v[72:75], v[164:167], v[218:221], v[72:75]
	v_mfma_f32_16x16x32_bf16 v[68:71], v[172:175], v[218:221], v[68:71]
	v_mfma_f32_16x16x32_bf16 v[120:123], v[168:171], v[184:187], v[120:123]
	v_mfma_f32_16x16x32_bf16 v[116:119], v[176:179], v[184:187], v[116:119]
	v_mfma_f32_16x16x32_bf16 v[104:107], v[168:171], v[192:195], v[104:107]
	v_mfma_f32_16x16x32_bf16 v[100:103], v[176:179], v[192:195], v[100:103]
	v_mfma_f32_16x16x32_bf16 v[88:91], v[168:171], v[214:217], v[88:91]
	v_mfma_f32_16x16x32_bf16 v[84:87], v[176:179], v[214:217], v[84:87]
	v_mfma_f32_16x16x32_bf16 v[72:75], v[168:171], v[222:225], v[72:75]
	v_mfma_f32_16x16x32_bf16 v[68:71], v[176:179], v[222:225], v[68:71]
	s_setprio 0
	s_barrier
	s_add_u32 s42, s40, 0x8000
	s_addc_u32 s43, s41, 0
	s_add_i32 s59, s59, s44
	s_mov_b32 m0, s59
	ds_read_b128 v[180:183], v151 offset:49152
	ds_read_b128 v[184:187], v151 offset:50176
	ds_read_b128 v[188:191], v151 offset:51200
	ds_read_b128 v[192:195], v151 offset:52224
	ds_read_b128 v[202:205], v151 offset:53248
	ds_read_b128 v[214:217], v151 offset:54272
	ds_read_b128 v[218:221], v151 offset:55296
	ds_read_b128 v[222:225], v151 offset:56320
	global_load_lds_dwordx4 v2, s[42:43]
	s_add_i32 m0, s59, 0x2000
	s_add_u32 s40, s40, 0xc000
	v_lshl_add_u64 v[230:231], s[42:43], 0, v[132:133]
	s_addc_u32 s41, s41, 0
	s_add_i32 s42, s60, s44
	global_load_lds_dwordx4 v[230:231], off
	s_mov_b32 m0, s42
	v_lshl_add_u64 v[226:227], v[226:227], 0, s[4:5]
	global_load_lds_dwordx4 v2, s[40:41]
	s_add_i32 m0, s42, 0x2000
	s_nop 0
	global_load_lds_dwordx4 v132, s[40:41]
	s_mov_b32 m0, s49
	s_nop 0
	global_load_lds_dwordx4 v[226:227], off
	v_lshl_add_u64 v[226:227], v[228:229], 0, s[4:5]
	s_mov_b32 m0, s50
	s_nop 0
	global_load_lds_dwordx4 v[226:227], off
	s_waitcnt vmcnt(8)
	s_waitcnt lgkmcnt(0)
	s_barrier
	s_setprio 1
	s_waitcnt lgkmcnt(0)
	v_mfma_f32_16x16x32_bf16 v[64:67], v[142:145], v[180:183], v[64:67]
	v_mfma_f32_16x16x32_bf16 v[60:63], v[156:159], v[180:183], v[60:63]
	v_mfma_f32_16x16x32_bf16 v[48:51], v[142:145], v[188:191], v[48:51]
	v_mfma_f32_16x16x32_bf16 v[44:47], v[156:159], v[188:191], v[44:47]
	v_mfma_f32_16x16x32_bf16 v[32:35], v[142:145], v[202:205], v[32:35]
	v_mfma_f32_16x16x32_bf16 v[28:31], v[156:159], v[202:205], v[28:31]
	v_mfma_f32_16x16x32_bf16 v[16:19], v[142:145], v[218:221], v[16:19]
	v_mfma_f32_16x16x32_bf16 v[12:15], v[156:159], v[218:221], v[12:15]
	v_mfma_f32_16x16x32_bf16 v[64:67], v[152:155], v[184:187], v[64:67]
	v_mfma_f32_16x16x32_bf16 v[60:63], v[160:163], v[184:187], v[60:63]
	v_mfma_f32_16x16x32_bf16 v[48:51], v[152:155], v[192:195], v[48:51]
	v_mfma_f32_16x16x32_bf16 v[44:47], v[160:163], v[192:195], v[44:47]
	v_mfma_f32_16x16x32_bf16 v[32:35], v[152:155], v[214:217], v[32:35]
	v_mfma_f32_16x16x32_bf16 v[28:31], v[160:163], v[214:217], v[28:31]
	v_mfma_f32_16x16x32_bf16 v[16:19], v[152:155], v[222:225], v[16:19]
	v_mfma_f32_16x16x32_bf16 v[12:15], v[160:163], v[222:225], v[12:15]
	s_setprio 0
	s_setprio 1
	v_mfma_f32_16x16x32_bf16 v[56:59], v[164:167], v[180:183], v[56:59]
	v_mfma_f32_16x16x32_bf16 v[52:55], v[172:175], v[180:183], v[52:55]
	v_mfma_f32_16x16x32_bf16 v[40:43], v[164:167], v[188:191], v[40:43]
	v_mfma_f32_16x16x32_bf16 v[36:39], v[172:175], v[188:191], v[36:39]
	v_mfma_f32_16x16x32_bf16 v[24:27], v[164:167], v[202:205], v[24:27]
	v_mfma_f32_16x16x32_bf16 v[20:23], v[172:175], v[202:205], v[20:23]
	v_mfma_f32_16x16x32_bf16 v[8:11], v[164:167], v[218:221], v[8:11]
	v_mfma_f32_16x16x32_bf16 v[4:7], v[172:175], v[218:221], v[4:7]
	v_mfma_f32_16x16x32_bf16 v[56:59], v[168:171], v[184:187], v[56:59]
	v_mfma_f32_16x16x32_bf16 v[52:55], v[176:179], v[184:187], v[52:55]
	v_mfma_f32_16x16x32_bf16 v[40:43], v[168:171], v[192:195], v[40:43]
	v_mfma_f32_16x16x32_bf16 v[36:39], v[176:179], v[192:195], v[36:39]
	v_mfma_f32_16x16x32_bf16 v[24:27], v[168:171], v[214:217], v[24:27]
	v_mfma_f32_16x16x32_bf16 v[20:23], v[176:179], v[214:217], v[20:23]
	v_mfma_f32_16x16x32_bf16 v[8:11], v[168:171], v[222:225], v[8:11]
	v_mfma_f32_16x16x32_bf16 v[4:7], v[176:179], v[222:225], v[4:7]
	s_setprio 0
	s_barrier
	s_add_i32 s58, s58, 2
	s_add_u32 s56, s56, 0x10000
	s_addc_u32 s57, s57, 0
	s_add_u32 s34, s34, 0x100
	s_addc_u32 s35, s35, 0
	s_cmp_gt_u32 s58, 29
	s_cbranch_scc0 .LBB0_326
	s_and_b64 vcc, exec, s[6:7]
	s_cbranch_vccz .LBB0_329
	s_barrier

.LBB0_366:
	s_add_u32 s6, s0, 0xfff80080
	s_addc_u32 s7, s1, -1
	s_add_i32 s62, 0, 0x10000
	s_cmp_eq_u32 s61, 28
	s_cselect_b32 s9, s43, s7
	s_cselect_b32 s8, s51, s6
	v_add_u32_e32 v146, s62, v150
	s_cselect_b32 s7, s49, s60
	s_cselect_b32 s6, s58, s59
	s_add_i32 s64, 0, 0x14000
	ds_read_b128 v[142:145], v146
	ds_read_b128 v[156:159], v146 offset:1024
	ds_read_b128 v[160:163], v146 offset:2048
	ds_read_b128 v[164:167], v146 offset:3072
	v_add_u32_e32 v146, s64, v150
	ds_read_b128 v[168:171], v146
	ds_read_b128 v[172:175], v146 offset:1024
	ds_read_b128 v[176:179], v146 offset:2048
	ds_read_b128 v[180:183], v146 offset:3072
	s_add_i32 m0, s13, 0xc000
	ds_read_b128 v[184:187], v154
	ds_read_b128 v[188:191], v154 offset:1024
	ds_read_b128 v[192:195], v154 offset:2048
	ds_read_b128 v[202:205], v154 offset:3072
	ds_read_b128 v[214:217], v154 offset:4096
	ds_read_b128 v[218:221], v154 offset:5120
	ds_read_b128 v[222:225], v154 offset:6144
	ds_read_b128 v[226:229], v154 offset:7168
	global_load_lds_dwordx4 v138, s[0:1]
	s_add_i32 m0, s13, 0xe000
	s_nop 0
	global_load_lds_dwordx4 v140, s[0:1]
	s_waitcnt vmcnt(8)
	s_waitcnt lgkmcnt(0)
	s_barrier
	s_setprio 1
	s_waitcnt lgkmcnt(0)
	v_mfma_f32_16x16x32_bf16 v[128:131], v[142:145], v[184:187], v[128:131]
	v_mfma_f32_16x16x32_bf16 v[124:127], v[160:163], v[184:187], v[124:127]
	v_mfma_f32_16x16x32_bf16 v[112:115], v[142:145], v[192:195], v[112:115]
	v_mfma_f32_16x16x32_bf16 v[108:111], v[160:163], v[192:195], v[108:111]
	v_mfma_f32_16x16x32_bf16 v[96:99], v[142:145], v[214:217], v[96:99]
	v_mfma_f32_16x16x32_bf16 v[92:95], v[160:163], v[214:217], v[92:95]
	v_mfma_f32_16x16x32_bf16 v[80:83], v[142:145], v[222:225], v[80:83]
	v_mfma_f32_16x16x32_bf16 v[76:79], v[160:163], v[222:225], v[76:79]
	v_mfma_f32_16x16x32_bf16 v[128:131], v[156:159], v[188:191], v[128:131]
	v_mfma_f32_16x16x32_bf16 v[124:127], v[164:167], v[188:191], v[124:127]
	v_mfma_f32_16x16x32_bf16 v[112:115], v[156:159], v[202:205], v[112:115]
	v_mfma_f32_16x16x32_bf16 v[108:111], v[164:167], v[202:205], v[108:111]
	v_mfma_f32_16x16x32_bf16 v[96:99], v[156:159], v[218:221], v[96:99]
	v_mfma_f32_16x16x32_bf16 v[92:95], v[164:167], v[218:221], v[92:95]
	v_mfma_f32_16x16x32_bf16 v[80:83], v[156:159], v[226:229], v[80:83]
	v_mfma_f32_16x16x32_bf16 v[76:79], v[164:167], v[226:229], v[76:79]
	s_setprio 0
	s_setprio 1
	v_mfma_f32_16x16x32_bf16 v[120:123], v[168:171], v[184:187], v[120:123]
	v_mfma_f32_16x16x32_bf16 v[116:119], v[176:179], v[184:187], v[116:119]
	v_mfma_f32_16x16x32_bf16 v[104:107], v[168:171], v[192:195], v[104:107]
	v_mfma_f32_16x16x32_bf16 v[100:103], v[176:179], v[192:195], v[100:103]
	v_mfma_f32_16x16x32_bf16 v[88:91], v[168:171], v[214:217], v[88:91]
	v_mfma_f32_16x16x32_bf16 v[84:87], v[176:179], v[214:217], v[84:87]
	v_mfma_f32_16x16x32_bf16 v[72:75], v[168:171], v[222:225], v[72:75]
	v_mfma_f32_16x16x32_bf16 v[68:71], v[176:179], v[222:225], v[68:71]
	v_mfma_f32_16x16x32_bf16 v[120:123], v[172:175], v[188:191], v[120:123]
	v_mfma_f32_16x16x32_bf16 v[116:119], v[180:183], v[188:191], v[116:119]
	v_mfma_f32_16x16x32_bf16 v[104:107], v[172:175], v[202:205], v[104:107]
	v_mfma_f32_16x16x32_bf16 v[100:103], v[180:183], v[202:205], v[100:103]
	v_mfma_f32_16x16x32_bf16 v[88:91], v[172:175], v[218:221], v[88:91]
	v_mfma_f32_16x16x32_bf16 v[84:87], v[180:183], v[218:221], v[84:87]
	v_mfma_f32_16x16x32_bf16 v[72:75], v[172:175], v[226:229], v[72:75]
	v_mfma_f32_16x16x32_bf16 v[68:71], v[180:183], v[226:229], v[68:71]
	s_setprio 0
	s_barrier
	s_add_i32 s62, s62, s12
	s_mov_b32 m0, s62
	ds_read_b128 v[184:187], v154 offset:16384
	ds_read_b128 v[188:191], v154 offset:17408
	ds_read_b128 v[192:195], v154 offset:18432
	ds_read_b128 v[202:205], v154 offset:19456
	ds_read_b128 v[214:217], v154 offset:20480
	ds_read_b128 v[218:221], v154 offset:21504
	ds_read_b128 v[222:225], v154 offset:22528
	ds_read_b128 v[226:229], v154 offset:23552
	global_load_lds_dwordx4 v2, s[6:7]
	s_add_i32 m0, s62, 0x2000
	s_add_u32 s62, s6, 0x4000
	s_addc_u32 s63, s7, 0
	s_add_i32 s64, s64, s12
	global_load_lds_dwordx4 v132, s[6:7]
	s_mov_b32 m0, s64
	v_lshl_add_u64 v[230:231], s[8:9], 0, v[134:135]
	global_load_lds_dwordx4 v2, s[62:63]
	s_add_i32 m0, s64, 0x2000
	s_nop 0
	global_load_lds_dwordx4 v132, s[62:63]
	v_lshl_add_u64 v[146:147], s[8:9], 0, v[136:137]
	s_mov_b32 m0, s13
	s_nop 0
	global_load_lds_dwordx4 v136, s[8:9]
	s_mov_b32 m0, s14
	s_nop 0
	global_load_lds_dwordx4 v134, s[8:9]
	s_waitcnt vmcnt(8)
	s_waitcnt lgkmcnt(0)
	s_barrier
	s_setprio 1
	s_waitcnt lgkmcnt(0)
	v_mfma_f32_16x16x32_bf16 v[64:67], v[142:145], v[184:187], v[64:67]
	v_mfma_f32_16x16x32_bf16 v[60:63], v[160:163], v[184:187], v[60:63]
	v_mfma_f32_16x16x32_bf16 v[48:51], v[142:145], v[192:195], v[48:51]
	v_mfma_f32_16x16x32_bf16 v[44:47], v[160:163], v[192:195], v[44:47]
	v_mfma_f32_16x16x32_bf16 v[32:35], v[142:145], v[214:217], v[32:35]
	v_mfma_f32_16x16x32_bf16 v[28:31], v[160:163], v[214:217], v[28:31]
	v_mfma_f32_16x16x32_bf16 v[16:19], v[142:145], v[222:225], v[16:19]
	v_mfma_f32_16x16x32_bf16 v[12:15], v[160:163], v[222:225], v[12:15]
	v_mfma_f32_16x16x32_bf16 v[64:67], v[156:159], v[188:191], v[64:67]
	v_mfma_f32_16x16x32_bf16 v[60:63], v[164:167], v[188:191], v[60:63]
	v_mfma_f32_16x16x32_bf16 v[48:51], v[156:159], v[202:205], v[48:51]
	v_mfma_f32_16x16x32_bf16 v[44:47], v[164:167], v[202:205], v[44:47]
	v_mfma_f32_16x16x32_bf16 v[32:35], v[156:159], v[218:221], v[32:35]
	v_mfma_f32_16x16x32_bf16 v[28:31], v[164:167], v[218:221], v[28:31]
	v_mfma_f32_16x16x32_bf16 v[16:19], v[156:159], v[226:229], v[16:19]
	v_mfma_f32_16x16x32_bf16 v[12:15], v[164:167], v[226:229], v[12:15]
	s_setprio 0
	s_setprio 1
	v_mfma_f32_16x16x32_bf16 v[56:59], v[168:171], v[184:187], v[56:59]
	v_mfma_f32_16x16x32_bf16 v[52:55], v[176:179], v[184:187], v[52:55]
	v_mfma_f32_16x16x32_bf16 v[40:43], v[168:171], v[192:195], v[40:43]
	v_mfma_f32_16x16x32_bf16 v[36:39], v[176:179], v[192:195], v[36:39]
	v_mfma_f32_16x16x32_bf16 v[24:27], v[168:171], v[214:217], v[24:27]
	v_mfma_f32_16x16x32_bf16 v[20:23], v[176:179], v[214:217], v[20:23]
	v_mfma_f32_16x16x32_bf16 v[8:11], v[168:171], v[222:225], v[8:11]
	v_mfma_f32_16x16x32_bf16 v[4:7], v[176:179], v[222:225], v[4:7]
	v_mfma_f32_16x16x32_bf16 v[56:59], v[172:175], v[188:191], v[56:59]
	v_mfma_f32_16x16x32_bf16 v[52:55], v[180:183], v[188:191], v[52:55]
	v_mfma_f32_16x16x32_bf16 v[40:43], v[172:175], v[202:205], v[40:43]
	v_mfma_f32_16x16x32_bf16 v[36:39], v[180:183], v[202:205], v[36:39]
	v_mfma_f32_16x16x32_bf16 v[24:27], v[172:175], v[218:221], v[24:27]
	v_mfma_f32_16x16x32_bf16 v[20:23], v[180:183], v[218:221], v[20:23]
	v_mfma_f32_16x16x32_bf16 v[8:11], v[172:175], v[226:229], v[8:11]
	v_mfma_f32_16x16x32_bf16 v[4:7], v[180:183], v[226:229], v[4:7]
	s_setprio 0
	s_barrier
	s_add_i32 s62, 0, 0x18000
	v_add_u32_e32 v148, s62, v150
	s_add_i32 s63, 0, 0x1c000
	ds_read_b128 v[142:145], v148
	ds_read_b128 v[156:159], v148 offset:1024
	ds_read_b128 v[160:163], v148 offset:2048
	ds_read_b128 v[164:167], v148 offset:3072
	v_add_u32_e32 v148, s63, v150
	ds_read_b128 v[168:171], v148
	ds_read_b128 v[172:175], v148 offset:1024
	ds_read_b128 v[176:179], v148 offset:2048
	ds_read_b128 v[180:183], v148 offset:3072
	s_add_u32 s8, s8, 0x80000
	s_addc_u32 s9, s9, 0
	s_mov_b32 m0, s15
	ds_read_b128 v[184:187], v154 offset:32768
	ds_read_b128 v[188:191], v154 offset:33792
	ds_read_b128 v[192:195], v154 offset:34816
	ds_read_b128 v[202:205], v154 offset:35840
	ds_read_b128 v[214:217], v154 offset:36864
	ds_read_b128 v[218:221], v154 offset:37888
	ds_read_b128 v[222:225], v154 offset:38912
	ds_read_b128 v[226:229], v154 offset:39936
	global_load_lds_dwordx4 v136, s[8:9]
	s_mov_b32 m0, s22
	s_nop 0
	global_load_lds_dwordx4 v134, s[8:9]
	s_waitcnt vmcnt(8)
	s_waitcnt lgkmcnt(0)
	s_barrier
	s_setprio 1
	s_waitcnt lgkmcnt(0)
	v_mfma_f32_16x16x32_bf16 v[128:131], v[142:145], v[184:187], v[128:131]
	v_mfma_f32_16x16x32_bf16 v[124:127], v[160:163], v[184:187], v[124:127]
	v_mfma_f32_16x16x32_bf16 v[112:115], v[142:145], v[192:195], v[112:115]
	v_mfma_f32_16x16x32_bf16 v[108:111], v[160:163], v[192:195], v[108:111]
	v_mfma_f32_16x16x32_bf16 v[96:99], v[142:145], v[214:217], v[96:99]
	v_mfma_f32_16x16x32_bf16 v[92:95], v[160:163], v[214:217], v[92:95]
	v_mfma_f32_16x16x32_bf16 v[80:83], v[142:145], v[222:225], v[80:83]
	v_mfma_f32_16x16x32_bf16 v[76:79], v[160:163], v[222:225], v[76:79]
	v_mfma_f32_16x16x32_bf16 v[128:131], v[156:159], v[188:191], v[128:131]
	v_mfma_f32_16x16x32_bf16 v[124:127], v[164:167], v[188:191], v[124:127]
	v_mfma_f32_16x16x32_bf16 v[112:115], v[156:159], v[202:205], v[112:115]
	v_mfma_f32_16x16x32_bf16 v[108:111], v[164:167], v[202:205], v[108:111]
	v_mfma_f32_16x16x32_bf16 v[96:99], v[156:159], v[218:221], v[96:99]
	v_mfma_f32_16x16x32_bf16 v[92:95], v[164:167], v[218:221], v[92:95]
	v_mfma_f32_16x16x32_bf16 v[80:83], v[156:159], v[226:229], v[80:83]
	v_mfma_f32_16x16x32_bf16 v[76:79], v[164:167], v[226:229], v[76:79]
	s_setprio 0
	s_setprio 1
	v_mfma_f32_16x16x32_bf16 v[120:123], v[168:171], v[184:187], v[120:123]
	v_mfma_f32_16x16x32_bf16 v[116:119], v[176:179], v[184:187], v[116:119]
	v_mfma_f32_16x16x32_bf16 v[104:107], v[168:171], v[192:195], v[104:107]
	v_mfma_f32_16x16x32_bf16 v[100:103], v[176:179], v[192:195], v[100:103]
	v_mfma_f32_16x16x32_bf16 v[88:91], v[168:171], v[214:217], v[88:91]
	v_mfma_f32_16x16x32_bf16 v[84:87], v[176:179], v[214:217], v[84:87]
	v_mfma_f32_16x16x32_bf16 v[72:75], v[168:171], v[222:225], v[72:75]
	v_mfma_f32_16x16x32_bf16 v[68:71], v[176:179], v[222:225], v[68:71]
	v_mfma_f32_16x16x32_bf16 v[120:123], v[172:175], v[188:191], v[120:123]
	v_mfma_f32_16x16x32_bf16 v[116:119], v[180:183], v[188:191], v[116:119]
	v_mfma_f32_16x16x32_bf16 v[104:107], v[172:175], v[202:205], v[104:107]
	v_mfma_f32_16x16x32_bf16 v[100:103], v[180:183], v[202:205], v[100:103]
	v_mfma_f32_16x16x32_bf16 v[88:91], v[172:175], v[218:221], v[88:91]
	v_mfma_f32_16x16x32_bf16 v[84:87], v[180:183], v[218:221], v[84:87]
	v_mfma_f32_16x16x32_bf16 v[72:75], v[172:175], v[226:229], v[72:75]
	v_mfma_f32_16x16x32_bf16 v[68:71], v[180:183], v[226:229], v[68:71]
	s_setprio 0
	s_barrier
	s_add_u32 s8, s6, 0x8000
	s_addc_u32 s9, s7, 0
	s_add_i32 s62, s62, s12
	s_mov_b32 m0, s62
	ds_read_b128 v[184:187], v154 offset:49152
	ds_read_b128 v[188:191], v154 offset:50176
	ds_read_b128 v[192:195], v154 offset:51200
	ds_read_b128 v[202:205], v154 offset:52224
	ds_read_b128 v[214:217], v154 offset:53248
	ds_read_b128 v[218:221], v154 offset:54272
	ds_read_b128 v[222:225], v154 offset:55296
	ds_read_b128 v[226:229], v154 offset:56320
	global_load_lds_dwordx4 v2, s[8:9]
	s_add_i32 m0, s62, 0x2000
	s_add_u32 s6, s6, 0xc000
	v_lshl_add_u64 v[232:233], s[8:9], 0, v[132:133]
	s_addc_u32 s7, s7, 0
	s_add_i32 s8, s63, s12
	global_load_lds_dwordx4 v[232:233], off
	s_mov_b32 m0, s8
	v_lshl_add_u64 v[146:147], v[146:147], 0, s[4:5]
	global_load_lds_dwordx4 v2, s[6:7]
	s_add_i32 m0, s8, 0x2000
	s_nop 0
	global_load_lds_dwordx4 v132, s[6:7]
	s_mov_b32 m0, s34
	s_nop 0
	global_load_lds_dwordx4 v[146:147], off
	v_lshl_add_u64 v[146:147], v[230:231], 0, s[4:5]
	s_mov_b32 m0, s35
	s_nop 0
	global_load_lds_dwordx4 v[146:147], off
	s_waitcnt vmcnt(8)
	s_waitcnt lgkmcnt(0)
	s_barrier
	s_setprio 1
	s_waitcnt lgkmcnt(0)
	v_mfma_f32_16x16x32_bf16 v[64:67], v[142:145], v[184:187], v[64:67]
	v_mfma_f32_16x16x32_bf16 v[60:63], v[160:163], v[184:187], v[60:63]
	v_mfma_f32_16x16x32_bf16 v[48:51], v[142:145], v[192:195], v[48:51]
	v_mfma_f32_16x16x32_bf16 v[44:47], v[160:163], v[192:195], v[44:47]
	v_mfma_f32_16x16x32_bf16 v[32:35], v[142:145], v[214:217], v[32:35]
	v_mfma_f32_16x16x32_bf16 v[28:31], v[160:163], v[214:217], v[28:31]
	v_mfma_f32_16x16x32_bf16 v[16:19], v[142:145], v[222:225], v[16:19]
	v_mfma_f32_16x16x32_bf16 v[12:15], v[160:163], v[222:225], v[12:15]
	v_mfma_f32_16x16x32_bf16 v[64:67], v[156:159], v[188:191], v[64:67]
	v_mfma_f32_16x16x32_bf16 v[60:63], v[164:167], v[188:191], v[60:63]
	v_mfma_f32_16x16x32_bf16 v[48:51], v[156:159], v[202:205], v[48:51]
	v_mfma_f32_16x16x32_bf16 v[44:47], v[164:167], v[202:205], v[44:47]
	v_mfma_f32_16x16x32_bf16 v[32:35], v[156:159], v[218:221], v[32:35]
	v_mfma_f32_16x16x32_bf16 v[28:31], v[164:167], v[218:221], v[28:31]
	v_mfma_f32_16x16x32_bf16 v[16:19], v[156:159], v[226:229], v[16:19]
	v_mfma_f32_16x16x32_bf16 v[12:15], v[164:167], v[226:229], v[12:15]
	s_setprio 0
	s_setprio 1
	v_mfma_f32_16x16x32_bf16 v[56:59], v[168:171], v[184:187], v[56:59]
	v_mfma_f32_16x16x32_bf16 v[52:55], v[176:179], v[184:187], v[52:55]
	v_mfma_f32_16x16x32_bf16 v[40:43], v[168:171], v[192:195], v[40:43]
	v_mfma_f32_16x16x32_bf16 v[36:39], v[176:179], v[192:195], v[36:39]
	v_mfma_f32_16x16x32_bf16 v[24:27], v[168:171], v[214:217], v[24:27]
	v_mfma_f32_16x16x32_bf16 v[20:23], v[176:179], v[214:217], v[20:23]
	v_mfma_f32_16x16x32_bf16 v[8:11], v[168:171], v[222:225], v[8:11]
	v_mfma_f32_16x16x32_bf16 v[4:7], v[176:179], v[222:225], v[4:7]
	v_mfma_f32_16x16x32_bf16 v[56:59], v[172:175], v[188:191], v[56:59]
	v_mfma_f32_16x16x32_bf16 v[52:55], v[180:183], v[188:191], v[52:55]
	v_mfma_f32_16x16x32_bf16 v[40:43], v[172:175], v[202:205], v[40:43]
	v_mfma_f32_16x16x32_bf16 v[36:39], v[180:183], v[202:205], v[36:39]
	v_mfma_f32_16x16x32_bf16 v[24:27], v[172:175], v[218:221], v[24:27]
	v_mfma_f32_16x16x32_bf16 v[20:23], v[180:183], v[218:221], v[20:23]
	v_mfma_f32_16x16x32_bf16 v[8:11], v[172:175], v[226:229], v[8:11]
	v_mfma_f32_16x16x32_bf16 v[4:7], v[180:183], v[226:229], v[4:7]
	s_setprio 0
	s_barrier
	s_add_i32 s61, s61, 2
	s_add_u32 s59, s59, 0x10000
	s_addc_u32 s60, s60, 0
	s_add_u32 s0, s0, 0x100
	s_addc_u32 s1, s1, 0
	s_cmp_gt_u32 s61, 29
	s_cbranch_scc0 .LBB0_366
	s_and_b64 vcc, exec, s[46:47]
	s_cbranch_vccz .LBB0_369
	s_barrier

.LBB0_733:
	s_add_u32 s48, s34, 0xfff80080
	s_addc_u32 s49, s35, -1
	s_add_i32 s69, 0, 0x10000
	s_cmp_eq_u32 s68, 28
	s_cselect_b32 s51, s13, s49
	s_cselect_b32 s50, s64, s48
	s_cselect_b32 s49, s9, s67
	s_cselect_b32 s48, s65, s66
	s_add_i32 s72, 0, 0x14000
	v_add_u32_e32 v136, s69, v204
	v_add_u32_e32 v160, s72, v204
	ds_read_b128 v[116:119], v136
	ds_read_b128 v[128:131], v136 offset:1024
	ds_read_b128 v[132:135], v136 offset:2048
	ds_read_b128 v[136:139], v136 offset:3072
	ds_read_b128 v[140:143], v160
	ds_read_b128 v[148:151], v160 offset:1024
	ds_read_b128 v[152:155], v160 offset:2048
	ds_read_b128 v[160:163], v160 offset:3072
	s_add_i32 m0, s55, 0xc000
	ds_read_b128 v[164:167], v244
	ds_read_b128 v[168:171], v244 offset:1024
	ds_read_b128 v[172:175], v244 offset:2048
	ds_read_b128 v[176:179], v244 offset:3072
	ds_read_b128 v[180:183], v244 offset:4096
	ds_read_b128 v[184:187], v244 offset:5120
	ds_read_b128 v[188:191], v244 offset:6144
	ds_read_b128 v[192:195], v244 offset:7168
	global_load_lds_dwordx4 v218, s[34:35]
	s_add_i32 m0, s55, 0xe000
	s_nop 0
	global_load_lds_dwordx4 v220, s[34:35]
	s_waitcnt vmcnt(8)
	s_waitcnt lgkmcnt(0)
	s_barrier
	s_setprio 1
	s_waitcnt lgkmcnt(0)
	v_mfma_f32_16x16x32_bf16 v[156:159], v[116:119], v[164:167], v[156:159]
	v_mfma_f32_16x16x32_bf16 v[144:147], v[132:135], v[164:167], v[144:147]
	v_mfma_f32_16x16x32_bf16 v[112:115], v[116:119], v[172:175], v[112:115]
	v_mfma_f32_16x16x32_bf16 v[108:111], v[132:135], v[172:175], v[108:111]
	v_mfma_f32_16x16x32_bf16 v[96:99], v[116:119], v[180:183], v[96:99]
	v_mfma_f32_16x16x32_bf16 v[92:95], v[132:135], v[180:183], v[92:95]
	v_mfma_f32_16x16x32_bf16 v[80:83], v[116:119], v[188:191], v[80:83]
	v_mfma_f32_16x16x32_bf16 v[76:79], v[132:135], v[188:191], v[76:79]
	v_mfma_f32_16x16x32_bf16 v[156:159], v[128:131], v[168:171], v[156:159]
	v_mfma_f32_16x16x32_bf16 v[144:147], v[136:139], v[168:171], v[144:147]
	v_mfma_f32_16x16x32_bf16 v[112:115], v[128:131], v[176:179], v[112:115]
	v_mfma_f32_16x16x32_bf16 v[108:111], v[136:139], v[176:179], v[108:111]
	v_mfma_f32_16x16x32_bf16 v[96:99], v[128:131], v[184:187], v[96:99]
	v_mfma_f32_16x16x32_bf16 v[92:95], v[136:139], v[184:187], v[92:95]
	v_mfma_f32_16x16x32_bf16 v[80:83], v[128:131], v[192:195], v[80:83]
	v_mfma_f32_16x16x32_bf16 v[76:79], v[136:139], v[192:195], v[76:79]
	s_setprio 0
	s_setprio 1
	v_mfma_f32_16x16x32_bf16 v[124:127], v[140:143], v[164:167], v[124:127]
	v_mfma_f32_16x16x32_bf16 v[120:123], v[152:155], v[164:167], v[120:123]
	v_mfma_f32_16x16x32_bf16 v[104:107], v[140:143], v[172:175], v[104:107]
	v_mfma_f32_16x16x32_bf16 v[100:103], v[152:155], v[172:175], v[100:103]
	v_mfma_f32_16x16x32_bf16 v[88:91], v[140:143], v[180:183], v[88:91]
	v_mfma_f32_16x16x32_bf16 v[84:87], v[152:155], v[180:183], v[84:87]
	v_mfma_f32_16x16x32_bf16 v[72:75], v[140:143], v[188:191], v[72:75]
	v_mfma_f32_16x16x32_bf16 v[68:71], v[152:155], v[188:191], v[68:71]
	v_mfma_f32_16x16x32_bf16 v[124:127], v[148:151], v[168:171], v[124:127]
	v_mfma_f32_16x16x32_bf16 v[120:123], v[160:163], v[168:171], v[120:123]
	v_mfma_f32_16x16x32_bf16 v[104:107], v[148:151], v[176:179], v[104:107]
	v_mfma_f32_16x16x32_bf16 v[100:103], v[160:163], v[176:179], v[100:103]
	v_mfma_f32_16x16x32_bf16 v[88:91], v[148:151], v[184:187], v[88:91]
	v_mfma_f32_16x16x32_bf16 v[84:87], v[160:163], v[184:187], v[84:87]
	v_mfma_f32_16x16x32_bf16 v[72:75], v[148:151], v[192:195], v[72:75]
	v_mfma_f32_16x16x32_bf16 v[68:71], v[160:163], v[192:195], v[68:71]
	s_setprio 0
	s_barrier
	s_add_i32 s69, s69, s52
	s_mov_b32 m0, s69
	ds_read_b128 v[164:167], v244 offset:16384
	ds_read_b128 v[168:171], v244 offset:17408
	ds_read_b128 v[172:175], v244 offset:18432
	ds_read_b128 v[176:179], v244 offset:19456
	ds_read_b128 v[180:183], v244 offset:20480
	ds_read_b128 v[184:187], v244 offset:21504
	ds_read_b128 v[188:191], v244 offset:22528
	ds_read_b128 v[192:195], v244 offset:23552
	global_load_lds_dwordx4 v2, s[48:49]
	s_add_i32 m0, s69, 0x2000
	s_add_u32 s70, s48, 0x4000
	s_addc_u32 s71, s49, 0
	s_add_i32 s69, s72, s52
	global_load_lds_dwordx4 v196, s[48:49]
	s_mov_b32 m0, s69
	v_lshl_add_u64 v[224:225], s[50:51], 0, v[214:215]
	global_load_lds_dwordx4 v2, s[70:71]
	s_add_i32 m0, s69, 0x2000
	s_nop 0
	global_load_lds_dwordx4 v196, s[70:71]
	v_lshl_add_u64 v[222:223], s[50:51], 0, v[216:217]
	s_mov_b32 m0, s55
	s_nop 0
	global_load_lds_dwordx4 v216, s[50:51]
	s_mov_b32 m0, s56
	s_nop 0
	global_load_lds_dwordx4 v214, s[50:51]
	s_waitcnt vmcnt(8)
	s_waitcnt lgkmcnt(0)
	s_barrier
	s_setprio 1
	s_waitcnt lgkmcnt(0)
	v_mfma_f32_16x16x32_bf16 v[64:67], v[116:119], v[164:167], v[64:67]
	v_mfma_f32_16x16x32_bf16 v[60:63], v[132:135], v[164:167], v[60:63]
	v_mfma_f32_16x16x32_bf16 v[48:51], v[116:119], v[172:175], v[48:51]
	v_mfma_f32_16x16x32_bf16 v[44:47], v[132:135], v[172:175], v[44:47]
	v_mfma_f32_16x16x32_bf16 v[32:35], v[116:119], v[180:183], v[32:35]
	v_mfma_f32_16x16x32_bf16 v[28:31], v[132:135], v[180:183], v[28:31]
	v_mfma_f32_16x16x32_bf16 v[16:19], v[116:119], v[188:191], v[16:19]
	v_mfma_f32_16x16x32_bf16 v[12:15], v[132:135], v[188:191], v[12:15]
	v_mfma_f32_16x16x32_bf16 v[64:67], v[128:131], v[168:171], v[64:67]
	v_mfma_f32_16x16x32_bf16 v[60:63], v[136:139], v[168:171], v[60:63]
	v_mfma_f32_16x16x32_bf16 v[48:51], v[128:131], v[176:179], v[48:51]
	v_mfma_f32_16x16x32_bf16 v[44:47], v[136:139], v[176:179], v[44:47]
	v_mfma_f32_16x16x32_bf16 v[32:35], v[128:131], v[184:187], v[32:35]
	v_mfma_f32_16x16x32_bf16 v[28:31], v[136:139], v[184:187], v[28:31]
	v_mfma_f32_16x16x32_bf16 v[16:19], v[128:131], v[192:195], v[16:19]
	v_mfma_f32_16x16x32_bf16 v[12:15], v[136:139], v[192:195], v[12:15]
	s_setprio 0
	s_setprio 1
	v_mfma_f32_16x16x32_bf16 v[56:59], v[140:143], v[164:167], v[56:59]
	v_mfma_f32_16x16x32_bf16 v[52:55], v[152:155], v[164:167], v[52:55]
	v_mfma_f32_16x16x32_bf16 v[40:43], v[140:143], v[172:175], v[40:43]
	v_mfma_f32_16x16x32_bf16 v[36:39], v[152:155], v[172:175], v[36:39]
	v_mfma_f32_16x16x32_bf16 v[24:27], v[140:143], v[180:183], v[24:27]
	v_mfma_f32_16x16x32_bf16 v[20:23], v[152:155], v[180:183], v[20:23]
	v_mfma_f32_16x16x32_bf16 v[8:11], v[140:143], v[188:191], v[8:11]
	v_mfma_f32_16x16x32_bf16 v[4:7], v[152:155], v[188:191], v[4:7]
	v_mfma_f32_16x16x32_bf16 v[56:59], v[148:151], v[168:171], v[56:59]
	v_mfma_f32_16x16x32_bf16 v[52:55], v[160:163], v[168:171], v[52:55]
	v_mfma_f32_16x16x32_bf16 v[40:43], v[148:151], v[176:179], v[40:43]
	v_mfma_f32_16x16x32_bf16 v[36:39], v[160:163], v[176:179], v[36:39]
	v_mfma_f32_16x16x32_bf16 v[24:27], v[148:151], v[184:187], v[24:27]
	v_mfma_f32_16x16x32_bf16 v[20:23], v[160:163], v[184:187], v[20:23]
	v_mfma_f32_16x16x32_bf16 v[8:11], v[148:151], v[192:195], v[8:11]
	v_mfma_f32_16x16x32_bf16 v[4:7], v[160:163], v[192:195], v[4:7]
	s_setprio 0
	s_barrier
	s_add_i32 s69, 0, 0x18000
	s_add_i32 s70, 0, 0x1c000
	v_add_u32_e32 v136, s69, v204
	v_add_u32_e32 v160, s70, v204
	ds_read_b128 v[116:119], v136
	ds_read_b128 v[128:131], v136 offset:1024
	ds_read_b128 v[132:135], v136 offset:2048
	ds_read_b128 v[136:139], v136 offset:3072
	ds_read_b128 v[140:143], v160
	ds_read_b128 v[148:151], v160 offset:1024
	ds_read_b128 v[152:155], v160 offset:2048
	ds_read_b128 v[160:163], v160 offset:3072
	s_add_u32 s50, s50, 0x80000
	s_addc_u32 s51, s51, 0
	s_mov_b32 m0, s57
	ds_read_b128 v[164:167], v244 offset:32768
	ds_read_b128 v[168:171], v244 offset:33792
	ds_read_b128 v[172:175], v244 offset:34816
	ds_read_b128 v[176:179], v244 offset:35840
	ds_read_b128 v[180:183], v244 offset:36864
	ds_read_b128 v[184:187], v244 offset:37888
	ds_read_b128 v[188:191], v244 offset:38912
	ds_read_b128 v[192:195], v244 offset:39936
	global_load_lds_dwordx4 v216, s[50:51]
	s_mov_b32 m0, s58
	s_nop 0
	global_load_lds_dwordx4 v214, s[50:51]
	s_waitcnt vmcnt(8)
	s_waitcnt lgkmcnt(0)
	s_barrier
	s_setprio 1
	s_waitcnt lgkmcnt(0)
	v_mfma_f32_16x16x32_bf16 v[156:159], v[116:119], v[164:167], v[156:159]
	v_mfma_f32_16x16x32_bf16 v[144:147], v[132:135], v[164:167], v[144:147]
	v_mfma_f32_16x16x32_bf16 v[112:115], v[116:119], v[172:175], v[112:115]
	v_mfma_f32_16x16x32_bf16 v[108:111], v[132:135], v[172:175], v[108:111]
	v_mfma_f32_16x16x32_bf16 v[96:99], v[116:119], v[180:183], v[96:99]
	v_mfma_f32_16x16x32_bf16 v[92:95], v[132:135], v[180:183], v[92:95]
	v_mfma_f32_16x16x32_bf16 v[80:83], v[116:119], v[188:191], v[80:83]
	v_mfma_f32_16x16x32_bf16 v[76:79], v[132:135], v[188:191], v[76:79]
	v_mfma_f32_16x16x32_bf16 v[156:159], v[128:131], v[168:171], v[156:159]
	v_mfma_f32_16x16x32_bf16 v[144:147], v[136:139], v[168:171], v[144:147]
	v_mfma_f32_16x16x32_bf16 v[112:115], v[128:131], v[176:179], v[112:115]
	v_mfma_f32_16x16x32_bf16 v[108:111], v[136:139], v[176:179], v[108:111]
	v_mfma_f32_16x16x32_bf16 v[96:99], v[128:131], v[184:187], v[96:99]
	v_mfma_f32_16x16x32_bf16 v[92:95], v[136:139], v[184:187], v[92:95]
	v_mfma_f32_16x16x32_bf16 v[80:83], v[128:131], v[192:195], v[80:83]
	v_mfma_f32_16x16x32_bf16 v[76:79], v[136:139], v[192:195], v[76:79]
	s_setprio 0
	s_setprio 1
	v_mfma_f32_16x16x32_bf16 v[124:127], v[140:143], v[164:167], v[124:127]
	v_mfma_f32_16x16x32_bf16 v[120:123], v[152:155], v[164:167], v[120:123]
	v_mfma_f32_16x16x32_bf16 v[104:107], v[140:143], v[172:175], v[104:107]
	v_mfma_f32_16x16x32_bf16 v[100:103], v[152:155], v[172:175], v[100:103]
	v_mfma_f32_16x16x32_bf16 v[88:91], v[140:143], v[180:183], v[88:91]
	v_mfma_f32_16x16x32_bf16 v[84:87], v[152:155], v[180:183], v[84:87]
	v_mfma_f32_16x16x32_bf16 v[72:75], v[140:143], v[188:191], v[72:75]
	v_mfma_f32_16x16x32_bf16 v[68:71], v[152:155], v[188:191], v[68:71]
	v_mfma_f32_16x16x32_bf16 v[124:127], v[148:151], v[168:171], v[124:127]
	v_mfma_f32_16x16x32_bf16 v[120:123], v[160:163], v[168:171], v[120:123]
	v_mfma_f32_16x16x32_bf16 v[104:107], v[148:151], v[176:179], v[104:107]
	v_mfma_f32_16x16x32_bf16 v[100:103], v[160:163], v[176:179], v[100:103]
	v_mfma_f32_16x16x32_bf16 v[88:91], v[148:151], v[184:187], v[88:91]
	v_mfma_f32_16x16x32_bf16 v[84:87], v[160:163], v[184:187], v[84:87]
	v_mfma_f32_16x16x32_bf16 v[72:75], v[148:151], v[192:195], v[72:75]
	v_mfma_f32_16x16x32_bf16 v[68:71], v[160:163], v[192:195], v[68:71]
	s_setprio 0
	s_barrier
	s_add_u32 s50, s48, 0x8000
	s_addc_u32 s51, s49, 0
	s_add_i32 s69, s69, s52
	s_mov_b32 m0, s69
	ds_read_b128 v[164:167], v244 offset:49152
	ds_read_b128 v[168:171], v244 offset:50176
	ds_read_b128 v[172:175], v244 offset:51200
	ds_read_b128 v[176:179], v244 offset:52224
	ds_read_b128 v[180:183], v244 offset:53248
	ds_read_b128 v[184:187], v244 offset:54272
	ds_read_b128 v[188:191], v244 offset:55296
	ds_read_b128 v[192:195], v244 offset:56320
	global_load_lds_dwordx4 v2, s[50:51]
	s_add_i32 m0, s69, 0x2000
	s_add_u32 s48, s48, 0xc000
	v_lshl_add_u64 v[226:227], s[50:51], 0, v[196:197]
	s_addc_u32 s49, s49, 0
	s_add_i32 s50, s70, s52
	global_load_lds_dwordx4 v[226:227], off
	s_mov_b32 m0, s50
	v_lshl_add_u64 v[222:223], v[222:223], 0, s[4:5]
	global_load_lds_dwordx4 v2, s[48:49]
	s_add_i32 m0, s50, 0x2000
	s_nop 0
	global_load_lds_dwordx4 v196, s[48:49]
	s_mov_b32 m0, s59
	s_nop 0
	global_load_lds_dwordx4 v[222:223], off
	v_lshl_add_u64 v[222:223], v[224:225], 0, s[4:5]
	s_mov_b32 m0, s60
	s_nop 0
	global_load_lds_dwordx4 v[222:223], off
	s_waitcnt vmcnt(8)
	s_waitcnt lgkmcnt(0)
	s_barrier
	s_setprio 1
	s_waitcnt lgkmcnt(0)
	v_mfma_f32_16x16x32_bf16 v[64:67], v[116:119], v[164:167], v[64:67]
	v_mfma_f32_16x16x32_bf16 v[60:63], v[132:135], v[164:167], v[60:63]
	v_mfma_f32_16x16x32_bf16 v[48:51], v[116:119], v[172:175], v[48:51]
	v_mfma_f32_16x16x32_bf16 v[44:47], v[132:135], v[172:175], v[44:47]
	v_mfma_f32_16x16x32_bf16 v[32:35], v[116:119], v[180:183], v[32:35]
	v_mfma_f32_16x16x32_bf16 v[28:31], v[132:135], v[180:183], v[28:31]
	v_mfma_f32_16x16x32_bf16 v[16:19], v[116:119], v[188:191], v[16:19]
	v_mfma_f32_16x16x32_bf16 v[12:15], v[132:135], v[188:191], v[12:15]
	v_mfma_f32_16x16x32_bf16 v[64:67], v[128:131], v[168:171], v[64:67]
	v_mfma_f32_16x16x32_bf16 v[60:63], v[136:139], v[168:171], v[60:63]
	v_mfma_f32_16x16x32_bf16 v[48:51], v[128:131], v[176:179], v[48:51]
	v_mfma_f32_16x16x32_bf16 v[44:47], v[136:139], v[176:179], v[44:47]
	v_mfma_f32_16x16x32_bf16 v[32:35], v[128:131], v[184:187], v[32:35]
	v_mfma_f32_16x16x32_bf16 v[28:31], v[136:139], v[184:187], v[28:31]
	v_mfma_f32_16x16x32_bf16 v[16:19], v[128:131], v[192:195], v[16:19]
	v_mfma_f32_16x16x32_bf16 v[12:15], v[136:139], v[192:195], v[12:15]
	s_setprio 0
	s_setprio 1
	v_mfma_f32_16x16x32_bf16 v[56:59], v[140:143], v[164:167], v[56:59]
	v_mfma_f32_16x16x32_bf16 v[52:55], v[152:155], v[164:167], v[52:55]
	v_mfma_f32_16x16x32_bf16 v[40:43], v[140:143], v[172:175], v[40:43]
	v_mfma_f32_16x16x32_bf16 v[36:39], v[152:155], v[172:175], v[36:39]
	v_mfma_f32_16x16x32_bf16 v[24:27], v[140:143], v[180:183], v[24:27]
	v_mfma_f32_16x16x32_bf16 v[20:23], v[152:155], v[180:183], v[20:23]
	v_mfma_f32_16x16x32_bf16 v[8:11], v[140:143], v[188:191], v[8:11]
	v_mfma_f32_16x16x32_bf16 v[4:7], v[152:155], v[188:191], v[4:7]
	v_mfma_f32_16x16x32_bf16 v[56:59], v[148:151], v[168:171], v[56:59]
	v_mfma_f32_16x16x32_bf16 v[52:55], v[160:163], v[168:171], v[52:55]
	v_mfma_f32_16x16x32_bf16 v[40:43], v[148:151], v[176:179], v[40:43]
	v_mfma_f32_16x16x32_bf16 v[36:39], v[160:163], v[176:179], v[36:39]
	v_mfma_f32_16x16x32_bf16 v[24:27], v[148:151], v[184:187], v[24:27]
	v_mfma_f32_16x16x32_bf16 v[20:23], v[160:163], v[184:187], v[20:23]
	v_mfma_f32_16x16x32_bf16 v[8:11], v[148:151], v[192:195], v[8:11]
	v_mfma_f32_16x16x32_bf16 v[4:7], v[160:163], v[192:195], v[4:7]
	s_setprio 0
	s_barrier
	s_add_i32 s68, s68, 2
	s_add_u32 s66, s66, 0x10000
	s_addc_u32 s67, s67, 0
	s_add_u32 s34, s34, 0x100
	s_addc_u32 s35, s35, 0
	s_cmp_gt_u32 s68, 29
	s_cbranch_scc0 .LBB0_733
	s_and_b64 vcc, exec, s[6:7]
	s_cbranch_vccz .LBB0_736
	s_barrier
